# GEMM K-loop MFMA loop-nest order Nnmb, k innermost
# speedup vs baseline: 1.0014x; 1.0014x over previous
; #define PG8_STAGE(bufoff, gbase, voff) do { _Pragma("unroll") for (int _i = 0; _i < 2; ++_i) \
;         __builtin_amdgcn_global_load_lds((const unsigned*)((const char*)(gbase) + (voff)[_i]), (PG8_LAS unsigned*)(lds + (bufoff) + ldsw + _i * 8192), 16, 0, 0); } while (0)
; #define PG8_LDA(dst, b, h) do { _Pragma("unroll") for (int m = 0; m < 4; ++m) _Pragma("unroll") for (int k = 0; k < 2; ++k) dst[m][k] = *(const PG8_LAS bf16x8*)(lds + PG8_SA(b, h) + aoff + m * 2048 + k * 1024); } while (0)
; #define PG8_LDB(dst, b, h) do { _Pragma("unroll") for (int n = 0; n < 2; ++n) _Pragma("unroll") for (int k = 0; k < 2; ++k) dst[n][k] = *(const PG8_LAS bf16x8*)(lds + PG8_SB(b, h) + boff + n * 2048 + k * 1024); } while (0)
; #define PG8_MMA(ai, bj, At, Bt) do { __builtin_amdgcn_s_setprio(1); _Pragma("unroll") for (int m = 0; m < 4; ++m) _Pragma("unroll") for (int n = 0; n < 2; ++n) _Pragma("unroll") for (int k = 0; k < 2; ++k) \
;         acc[ai][bj][m][n] = __builtin_amdgcn_mfma_f32_16x16x32_bf16(Bt[n][k], At[m][k], acc[ai][bj][m][n], 0, 0, 0); __builtin_amdgcn_s_setprio(0); } while (0)
; #define PG8_WAIT_V(n) asm volatile("s_waitcnt vmcnt(" #n ")" ::: "memory")
; #define PG8_WAIT_L(n) asm volatile("s_waitcnt lgkmcnt(" #n ")" ::: "memory")
; template <class Epi, class Sched, bool ALIGN_EPI = false, bool SP2 = false>
; __device__ __forceinline__ void gemm_phase(PG8_LAS unsigned char* lds, const Gemm g, const Sched& S, const Epi& E) {
;     ...
;             const bool last = (t == nt - 2);
;             const char* a1 = cA + (size_t)(t + 1) * kstep;
;             const char* a2 = last ? nA : cA + (size_t)(t + 2) * kstep; const char* b2 = last ? nB : cB + (size_t)(t + 2) * kstep;
;             const char* a3 = a2 + kstep; const char* b3 = b2 + kstep;
;             if (last && has_next) S.a_ready(nxt);
;             if constexpr (SP2) {
;             PG8_LDB(B0, 0, 0); PG8_LDB(B1, 0, 1); PG8_SCHED; PG8_LDA(At, 0, 0); PG8_STAGE(PG8_SA(1, 1), a1 + hstep, voffA);
;             PG8_WAIT_V(8); PG8_WAIT_L(0); PG8_BAR; PG8_MMA(0, 0, At, B0); PG8_MMA(0, 1, At, B1); PG8_BAR; PG8_SCHED;
;             PG8_LDA(At, 0, 1); PG8_STAGE(PG8_SB(0, 0), b2, voffB); PG8_STAGE(PG8_SB(0, 1), b2 + hstep, voffB); PG8_STAGE(PG8_SA(0, 0), a2, voffA);
;             PG8_WAIT_V(8); PG8_WAIT_L(0); PG8_BAR; PG8_MMA(1, 0, At, B0); PG8_MMA(1, 1, At, B1); PG8_BAR; PG8_SCHED;
.LBB0_132:
	s_add_u32 s18, s46, 0xfffc0080
	s_addc_u32 s38, s47, -1
	s_add_i32 s39, 0, 0x10000
	s_cmp_eq_u32 s85, 12
	s_cselect_b32 s81, s33, s38
	s_cselect_b32 s80, s73, s18
	v_add_u32_e32 v0, s39, v176
	s_cselect_b32 s45, s75, s84
	s_cselect_b32 s44, s82, s83
	s_add_i32 s18, 0, 0x14000
	ds_read_b128 v[144:147], v0
	ds_read_b128 v[148:151], v0 offset:1024
	ds_read_b128 v[152:155], v0 offset:2048
	ds_read_b128 v[156:159], v0 offset:3072
	v_add_u32_e32 v0, s18, v176
	ds_read_b128 v[160:163], v0
	ds_read_b128 v[164:167], v0 offset:1024
	ds_read_b128 v[168:171], v0 offset:2048
	ds_read_b128 v[172:175], v0 offset:3072
	v_lshl_add_u64 v[218:219], s[46:47], 0, v[140:141]
	s_add_i32 m0, s92, 0xc000
	ds_read_b128 v[180:183], v178
	ds_read_b128 v[184:187], v178 offset:1024
	ds_read_b128 v[188:191], v178 offset:2048
	ds_read_b128 v[192:195], v178 offset:3072
	ds_read_b128 v[202:205], v178 offset:4096
	ds_read_b128 v[206:209], v178 offset:5120
	ds_read_b128 v[210:213], v178 offset:6144
	ds_read_b128 v[214:217], v178 offset:7168
	global_load_lds_dwordx4 v[218:219], off
	v_lshl_add_u64 v[218:219], s[46:47], 0, v[142:143]
	s_add_i32 m0, s92, 0xe000
	s_nop 0
	global_load_lds_dwordx4 v[218:219], off
	s_waitcnt vmcnt(8)
	s_waitcnt lgkmcnt(0)
	s_barrier
	s_setprio 1
	s_waitcnt lgkmcnt(0)
	v_mfma_f32_16x16x32_bf16 v[118:121], v[144:147], v[180:183], v[118:121]
	v_mfma_f32_16x16x32_bf16 v[118:121], v[148:151], v[184:187], v[118:121]
	v_mfma_f32_16x16x32_bf16 v[126:129], v[160:163], v[180:183], v[126:129]
	v_mfma_f32_16x16x32_bf16 v[126:129], v[164:167], v[184:187], v[126:129]
	v_mfma_f32_16x16x32_bf16 v[102:105], v[144:147], v[188:191], v[102:105]
	v_mfma_f32_16x16x32_bf16 v[102:105], v[148:151], v[192:195], v[102:105]
	v_mfma_f32_16x16x32_bf16 v[110:113], v[160:163], v[188:191], v[110:113]
	v_mfma_f32_16x16x32_bf16 v[110:113], v[164:167], v[192:195], v[110:113]
	v_mfma_f32_16x16x32_bf16 v[86:89], v[144:147], v[202:205], v[86:89]
	v_mfma_f32_16x16x32_bf16 v[86:89], v[148:151], v[206:209], v[86:89]
	v_mfma_f32_16x16x32_bf16 v[94:97], v[160:163], v[202:205], v[94:97]
	v_mfma_f32_16x16x32_bf16 v[94:97], v[164:167], v[206:209], v[94:97]
	v_mfma_f32_16x16x32_bf16 v[70:73], v[144:147], v[210:213], v[70:73]
	v_mfma_f32_16x16x32_bf16 v[70:73], v[148:151], v[214:217], v[70:73]
	v_mfma_f32_16x16x32_bf16 v[78:81], v[160:163], v[210:213], v[78:81]
	v_mfma_f32_16x16x32_bf16 v[78:81], v[164:167], v[214:217], v[78:81]
	v_mfma_f32_16x16x32_bf16 v[114:117], v[152:155], v[180:183], v[114:117]
	v_mfma_f32_16x16x32_bf16 v[114:117], v[156:159], v[184:187], v[114:117]
	v_mfma_f32_16x16x32_bf16 v[122:125], v[168:171], v[180:183], v[122:125]
	v_mfma_f32_16x16x32_bf16 v[122:125], v[172:175], v[184:187], v[122:125]
	v_mfma_f32_16x16x32_bf16 v[98:101], v[152:155], v[188:191], v[98:101]
	v_mfma_f32_16x16x32_bf16 v[98:101], v[156:159], v[192:195], v[98:101]
	v_mfma_f32_16x16x32_bf16 v[106:109], v[168:171], v[188:191], v[106:109]
	v_mfma_f32_16x16x32_bf16 v[106:109], v[172:175], v[192:195], v[106:109]
	v_mfma_f32_16x16x32_bf16 v[82:85], v[152:155], v[202:205], v[82:85]
	v_mfma_f32_16x16x32_bf16 v[82:85], v[156:159], v[206:209], v[82:85]
	v_mfma_f32_16x16x32_bf16 v[90:93], v[168:171], v[202:205], v[90:93]
	v_mfma_f32_16x16x32_bf16 v[90:93], v[172:175], v[206:209], v[90:93]
	v_mfma_f32_16x16x32_bf16 v[66:69], v[152:155], v[210:213], v[66:69]
	v_mfma_f32_16x16x32_bf16 v[66:69], v[156:159], v[214:217], v[66:69]
	v_mfma_f32_16x16x32_bf16 v[74:77], v[168:171], v[210:213], v[74:77]
	v_mfma_f32_16x16x32_bf16 v[74:77], v[172:175], v[214:217], v[74:77]
	s_setprio 0
	s_barrier
	s_add_i32 s38, s39, s91
	v_lshl_add_u64 v[218:219], s[44:45], 0, v[134:135]
	s_mov_b32 m0, s38
	ds_read_b128 v[180:183], v178 offset:16384
	ds_read_b128 v[184:187], v178 offset:17408
	ds_read_b128 v[188:191], v178 offset:18432
	ds_read_b128 v[192:195], v178 offset:19456
	ds_read_b128 v[202:205], v178 offset:20480
	ds_read_b128 v[206:209], v178 offset:21504
	ds_read_b128 v[210:213], v178 offset:22528
	ds_read_b128 v[214:217], v178 offset:23552
	global_load_lds_dwordx4 v[218:219], off
	s_add_i32 m0, s38, 0x2000
	s_add_u32 s38, s44, 0x40000
	v_lshl_add_u64 v[220:221], s[44:45], 0, v[130:131]
	s_addc_u32 s39, s45, 0
	s_add_i32 s18, s18, s91
	global_load_lds_dwordx4 v[220:221], off
	v_lshl_add_u64 v[222:223], s[38:39], 0, v[134:135]
	s_mov_b32 m0, s18
	v_lshl_add_u64 v[224:225], s[80:81], 0, v[132:133]
	global_load_lds_dwordx4 v[222:223], off
	v_lshl_add_u64 v[222:223], s[38:39], 0, v[130:131]
	s_add_i32 m0, s18, 0x2000
	s_nop 0
	global_load_lds_dwordx4 v[222:223], off
	v_lshl_add_u64 v[222:223], s[80:81], 0, v[136:137]
	s_mov_b32 m0, s92
	s_nop 0
	global_load_lds_dwordx4 v[222:223], off
	s_mov_b32 m0, s93
	s_nop 0
	global_load_lds_dwordx4 v[224:225], off
	s_waitcnt vmcnt(8)
	s_waitcnt lgkmcnt(0)
	s_barrier
; #define PG8_STAGE(bufoff, gbase, voff) do { _Pragma("unroll") for (int _i = 0; _i < 2; ++_i) \
;         __builtin_amdgcn_global_load_lds((const unsigned*)((const char*)(gbase) + (voff)[_i]), (PG8_LAS unsigned*)(lds + (bufoff) + ldsw + _i * 8192), 16, 0, 0); } while (0)
; #define PG8_LDA(dst, b, h) do { _Pragma("unroll") for (int m = 0; m < 4; ++m) _Pragma("unroll") for (int k = 0; k < 2; ++k) dst[m][k] = *(const PG8_LAS bf16x8*)(lds + PG8_SA(b, h) + aoff + m * 2048 + k * 1024); } while (0)
; #define PG8_LDB(dst, b, h) do { _Pragma("unroll") for (int n = 0; n < 2; ++n) _Pragma("unroll") for (int k = 0; k < 2; ++k) dst[n][k] = *(const PG8_LAS bf16x8*)(lds + PG8_SB(b, h) + boff + n * 2048 + k * 1024); } while (0)
; #define PG8_MMA(ai, bj, At, Bt) do { __builtin_amdgcn_s_setprio(1); _Pragma("unroll") for (int m = 0; m < 4; ++m) _Pragma("unroll") for (int n = 0; n < 2; ++n) _Pragma("unroll") for (int k = 0; k < 2; ++k) \
;         acc[ai][bj][m][n] = __builtin_amdgcn_mfma_f32_16x16x32_bf16(Bt[n][k], At[m][k], acc[ai][bj][m][n], 0, 0, 0); __builtin_amdgcn_s_setprio(0); } while (0)
; #define PG8_WAIT_V(n) asm volatile("s_waitcnt vmcnt(" #n ")" ::: "memory")
; #define PG8_WAIT_L(n) asm volatile("s_waitcnt lgkmcnt(" #n ")" ::: "memory")
; #define PG8_BAR __builtin_amdgcn_s_barrier()
; #define PG8_SCHED __builtin_amdgcn_sched_barrier(0)
; template <class Epi, class Sched, bool ALIGN_EPI = false, bool SP2 = false>
; __device__ __forceinline__ void gemm_phase(PG8_LAS unsigned char* lds, const Gemm g, const Sched& S, const Epi& E) {
;     ...
;             PG8_WAIT_V(8); PG8_WAIT_L(0); PG8_BAR; PG8_MMA(1, 0, At, B0); PG8_MMA(1, 1, At, B1); PG8_BAR; PG8_SCHED;
;             PG8_LDB(B0, 1, 0); PG8_LDB(B1, 1, 1); PG8_SCHED; PG8_LDA(At, 1, 0); PG8_STAGE(PG8_SA(0, 1), a2 + hstep, voffA);
;             PG8_WAIT_V(8); PG8_WAIT_L(0); PG8_BAR; PG8_MMA(0, 0, At, B0); PG8_MMA(0, 1, At, B1); PG8_BAR; PG8_SCHED;
	s_setprio 1
	s_waitcnt lgkmcnt(0)
	v_mfma_f32_16x16x32_bf16 v[54:57], v[144:147], v[180:183], v[54:57]
	v_mfma_f32_16x16x32_bf16 v[54:57], v[148:151], v[184:187], v[54:57]
	v_mfma_f32_16x16x32_bf16 v[62:65], v[160:163], v[180:183], v[62:65]
	v_mfma_f32_16x16x32_bf16 v[62:65], v[164:167], v[184:187], v[62:65]
	v_mfma_f32_16x16x32_bf16 v[38:41], v[144:147], v[188:191], v[38:41]
	v_mfma_f32_16x16x32_bf16 v[38:41], v[148:151], v[192:195], v[38:41]
	v_mfma_f32_16x16x32_bf16 v[46:49], v[160:163], v[188:191], v[46:49]
	v_mfma_f32_16x16x32_bf16 v[46:49], v[164:167], v[192:195], v[46:49]
	v_mfma_f32_16x16x32_bf16 v[22:25], v[144:147], v[202:205], v[22:25]
	v_mfma_f32_16x16x32_bf16 v[22:25], v[148:151], v[206:209], v[22:25]
	v_mfma_f32_16x16x32_bf16 v[30:33], v[160:163], v[202:205], v[30:33]
	v_mfma_f32_16x16x32_bf16 v[30:33], v[164:167], v[206:209], v[30:33]
	v_mfma_f32_16x16x32_bf16 v[6:9], v[144:147], v[210:213], v[6:9]
	v_mfma_f32_16x16x32_bf16 v[6:9], v[148:151], v[214:217], v[6:9]
	v_mfma_f32_16x16x32_bf16 v[10:13], v[160:163], v[210:213], v[10:13]
	v_mfma_f32_16x16x32_bf16 v[10:13], v[164:167], v[214:217], v[10:13]
	v_mfma_f32_16x16x32_bf16 v[50:53], v[152:155], v[180:183], v[50:53]
	v_mfma_f32_16x16x32_bf16 v[50:53], v[156:159], v[184:187], v[50:53]
	v_mfma_f32_16x16x32_bf16 v[58:61], v[168:171], v[180:183], v[58:61]
	v_mfma_f32_16x16x32_bf16 v[58:61], v[172:175], v[184:187], v[58:61]
	v_mfma_f32_16x16x32_bf16 v[34:37], v[152:155], v[188:191], v[34:37]
	v_mfma_f32_16x16x32_bf16 v[34:37], v[156:159], v[192:195], v[34:37]
	v_mfma_f32_16x16x32_bf16 v[42:45], v[168:171], v[188:191], v[42:45]
	v_mfma_f32_16x16x32_bf16 v[42:45], v[172:175], v[192:195], v[42:45]
	v_mfma_f32_16x16x32_bf16 v[18:21], v[152:155], v[202:205], v[18:21]
	v_mfma_f32_16x16x32_bf16 v[18:21], v[156:159], v[206:209], v[18:21]
	v_mfma_f32_16x16x32_bf16 v[26:29], v[168:171], v[202:205], v[26:29]
	v_mfma_f32_16x16x32_bf16 v[26:29], v[172:175], v[206:209], v[26:29]
	v_mfma_f32_16x16x32_bf16 v[2:5], v[152:155], v[210:213], v[2:5]
	v_mfma_f32_16x16x32_bf16 v[2:5], v[156:159], v[214:217], v[2:5]
	v_mfma_f32_16x16x32_bf16 v[14:17], v[168:171], v[210:213], v[14:17]
	v_mfma_f32_16x16x32_bf16 v[14:17], v[172:175], v[214:217], v[14:17]
	s_setprio 0
	s_barrier
	s_add_i32 s18, 0, 0x18000
	v_add_u32_e32 v0, s18, v176
	s_add_i32 vcc_lo, 0, 0x1c000
	ds_read_b128 v[144:147], v0
	ds_read_b128 v[148:151], v0 offset:1024
	ds_read_b128 v[152:155], v0 offset:2048
	ds_read_b128 v[156:159], v0 offset:3072
	v_add_u32_e32 v0, vcc_lo, v176
	ds_read_b128 v[160:163], v0
	ds_read_b128 v[164:167], v0 offset:1024
	ds_read_b128 v[168:171], v0 offset:2048
	ds_read_b128 v[172:175], v0 offset:3072
	s_add_u32 s38, s80, 0x40000
	s_addc_u32 s39, s81, 0
	s_mov_b32 m0, s94
	v_lshl_add_u64 v[226:227], s[38:39], 0, v[136:137]
	ds_read_b128 v[180:183], v178 offset:32768
	ds_read_b128 v[184:187], v178 offset:33792
	ds_read_b128 v[188:191], v178 offset:34816
	ds_read_b128 v[192:195], v178 offset:35840
	ds_read_b128 v[202:205], v178 offset:36864
	ds_read_b128 v[206:209], v178 offset:37888
	ds_read_b128 v[210:213], v178 offset:38912
	ds_read_b128 v[214:217], v178 offset:39936
	global_load_lds_dwordx4 v[226:227], off
	v_lshl_add_u64 v[226:227], s[38:39], 0, v[132:133]
	s_mov_b32 m0, s95
	s_nop 0
	global_load_lds_dwordx4 v[226:227], off
	s_waitcnt vmcnt(8)
	s_waitcnt lgkmcnt(0)
	s_barrier
	s_setprio 1
	s_waitcnt lgkmcnt(0)
	v_mfma_f32_16x16x32_bf16 v[118:121], v[144:147], v[180:183], v[118:121]
	v_mfma_f32_16x16x32_bf16 v[118:121], v[148:151], v[184:187], v[118:121]
	v_mfma_f32_16x16x32_bf16 v[126:129], v[160:163], v[180:183], v[126:129]
	v_mfma_f32_16x16x32_bf16 v[126:129], v[164:167], v[184:187], v[126:129]
	v_mfma_f32_16x16x32_bf16 v[102:105], v[144:147], v[188:191], v[102:105]
	v_mfma_f32_16x16x32_bf16 v[102:105], v[148:151], v[192:195], v[102:105]
	v_mfma_f32_16x16x32_bf16 v[110:113], v[160:163], v[188:191], v[110:113]
	v_mfma_f32_16x16x32_bf16 v[110:113], v[164:167], v[192:195], v[110:113]
	v_mfma_f32_16x16x32_bf16 v[86:89], v[144:147], v[202:205], v[86:89]
	v_mfma_f32_16x16x32_bf16 v[86:89], v[148:151], v[206:209], v[86:89]
	v_mfma_f32_16x16x32_bf16 v[94:97], v[160:163], v[202:205], v[94:97]
	v_mfma_f32_16x16x32_bf16 v[94:97], v[164:167], v[206:209], v[94:97]
	v_mfma_f32_16x16x32_bf16 v[70:73], v[144:147], v[210:213], v[70:73]
	v_mfma_f32_16x16x32_bf16 v[70:73], v[148:151], v[214:217], v[70:73]
	v_mfma_f32_16x16x32_bf16 v[78:81], v[160:163], v[210:213], v[78:81]
	v_mfma_f32_16x16x32_bf16 v[78:81], v[164:167], v[214:217], v[78:81]
	v_mfma_f32_16x16x32_bf16 v[114:117], v[152:155], v[180:183], v[114:117]
	v_mfma_f32_16x16x32_bf16 v[114:117], v[156:159], v[184:187], v[114:117]
	v_mfma_f32_16x16x32_bf16 v[122:125], v[168:171], v[180:183], v[122:125]
	v_mfma_f32_16x16x32_bf16 v[122:125], v[172:175], v[184:187], v[122:125]
	v_mfma_f32_16x16x32_bf16 v[98:101], v[152:155], v[188:191], v[98:101]
	v_mfma_f32_16x16x32_bf16 v[98:101], v[156:159], v[192:195], v[98:101]
	v_mfma_f32_16x16x32_bf16 v[106:109], v[168:171], v[188:191], v[106:109]
	v_mfma_f32_16x16x32_bf16 v[106:109], v[172:175], v[192:195], v[106:109]
	v_mfma_f32_16x16x32_bf16 v[82:85], v[152:155], v[202:205], v[82:85]
	v_mfma_f32_16x16x32_bf16 v[82:85], v[156:159], v[206:209], v[82:85]
	v_mfma_f32_16x16x32_bf16 v[90:93], v[168:171], v[202:205], v[90:93]
	v_mfma_f32_16x16x32_bf16 v[90:93], v[172:175], v[206:209], v[90:93]
	v_mfma_f32_16x16x32_bf16 v[66:69], v[152:155], v[210:213], v[66:69]
	v_mfma_f32_16x16x32_bf16 v[66:69], v[156:159], v[214:217], v[66:69]
	v_mfma_f32_16x16x32_bf16 v[74:77], v[168:171], v[210:213], v[74:77]
	v_mfma_f32_16x16x32_bf16 v[74:77], v[172:175], v[214:217], v[74:77]
	s_setprio 0
	s_barrier
; #define PG8_STAGE(bufoff, gbase, voff) do { _Pragma("unroll") for (int _i = 0; _i < 2; ++_i) \
;         __builtin_amdgcn_global_load_lds((const unsigned*)((const char*)(gbase) + (voff)[_i]), (PG8_LAS unsigned*)(lds + (bufoff) + ldsw + _i * 8192), 16, 0, 0); } while (0)
; #define PG8_LDA(dst, b, h) do { _Pragma("unroll") for (int m = 0; m < 4; ++m) _Pragma("unroll") for (int k = 0; k < 2; ++k) dst[m][k] = *(const PG8_LAS bf16x8*)(lds + PG8_SA(b, h) + aoff + m * 2048 + k * 1024); } while (0)
; #define PG8_MMA(ai, bj, At, Bt) do { __builtin_amdgcn_s_setprio(1); _Pragma("unroll") for (int m = 0; m < 4; ++m) _Pragma("unroll") for (int n = 0; n < 2; ++n) _Pragma("unroll") for (int k = 0; k < 2; ++k) \
;         acc[ai][bj][m][n] = __builtin_amdgcn_mfma_f32_16x16x32_bf16(Bt[n][k], At[m][k], acc[ai][bj][m][n], 0, 0, 0); __builtin_amdgcn_s_setprio(0); } while (0)
; #define PG8_WAIT_V(n) asm volatile("s_waitcnt vmcnt(" #n ")" ::: "memory")
; #define PG8_WAIT_L(n) asm volatile("s_waitcnt lgkmcnt(" #n ")" ::: "memory")
; #define PG8_BAR __builtin_amdgcn_s_barrier()
; #define PG8_SCHED __builtin_amdgcn_sched_barrier(0)
; template <class Epi, class Sched, bool ALIGN_EPI = false, bool SP2 = false>
; __device__ __forceinline__ void gemm_phase(PG8_LAS unsigned char* lds, const Gemm g, const Sched& S, const Epi& E) {
;     ...
;             PG8_LDA(At, 1, 1); PG8_STAGE(PG8_SB(1, 0), b3, voffB); PG8_STAGE(PG8_SB(1, 1), b3 + hstep, voffB); PG8_STAGE(PG8_SA(1, 0), a3, voffA);
;             PG8_WAIT_V(8); PG8_WAIT_L(0); PG8_BAR; PG8_MMA(1, 0, At, B0); PG8_MMA(1, 1, At, B1); PG8_BAR; PG8_SCHED;
	s_add_i32 s18, s18, s91
	v_lshl_add_u64 v[218:219], v[218:219], 0, s[30:31]
	s_mov_b32 m0, s18
	ds_read_b128 v[180:183], v178 offset:49152
	ds_read_b128 v[184:187], v178 offset:50176
	ds_read_b128 v[188:191], v178 offset:51200
	ds_read_b128 v[192:195], v178 offset:52224
	ds_read_b128 v[202:205], v178 offset:53248
	ds_read_b128 v[206:209], v178 offset:54272
	ds_read_b128 v[210:213], v178 offset:55296
	ds_read_b128 v[214:217], v178 offset:56320
	global_load_lds_dwordx4 v[218:219], off
	s_add_i32 m0, s18, 0x2000
	s_add_u32 s38, s44, 0x40080
	v_lshl_add_u64 v[218:219], v[220:221], 0, s[30:31]
	s_addc_u32 s39, s45, 0
	s_add_i32 s18, vcc_lo, s91
	global_load_lds_dwordx4 v[218:219], off
	v_lshl_add_u64 v[218:219], s[38:39], 0, v[134:135]
	s_mov_b32 m0, s18
	s_nop 0
	global_load_lds_dwordx4 v[218:219], off
	v_lshl_add_u64 v[218:219], s[38:39], 0, v[130:131]
	s_add_i32 m0, s18, 0x2000
	s_nop 0
	global_load_lds_dwordx4 v[218:219], off
	v_lshl_add_u64 v[218:219], v[222:223], 0, s[30:31]
	s_mov_b32 m0, s7
	s_nop 0
	global_load_lds_dwordx4 v[218:219], off
	v_lshl_add_u64 v[218:219], v[224:225], 0, s[30:31]
	s_mov_b32 m0, s96
	s_nop 0
	global_load_lds_dwordx4 v[218:219], off
	s_waitcnt vmcnt(8)
	s_waitcnt lgkmcnt(0)
	s_barrier
	s_setprio 1
	s_waitcnt lgkmcnt(0)
	v_mfma_f32_16x16x32_bf16 v[54:57], v[144:147], v[180:183], v[54:57]
	v_mfma_f32_16x16x32_bf16 v[54:57], v[148:151], v[184:187], v[54:57]
	v_mfma_f32_16x16x32_bf16 v[62:65], v[160:163], v[180:183], v[62:65]
	v_mfma_f32_16x16x32_bf16 v[62:65], v[164:167], v[184:187], v[62:65]
	v_mfma_f32_16x16x32_bf16 v[38:41], v[144:147], v[188:191], v[38:41]
	v_mfma_f32_16x16x32_bf16 v[38:41], v[148:151], v[192:195], v[38:41]
	v_mfma_f32_16x16x32_bf16 v[46:49], v[160:163], v[188:191], v[46:49]
	v_mfma_f32_16x16x32_bf16 v[46:49], v[164:167], v[192:195], v[46:49]
	v_mfma_f32_16x16x32_bf16 v[22:25], v[144:147], v[202:205], v[22:25]
	v_mfma_f32_16x16x32_bf16 v[22:25], v[148:151], v[206:209], v[22:25]
	v_mfma_f32_16x16x32_bf16 v[30:33], v[160:163], v[202:205], v[30:33]
	v_mfma_f32_16x16x32_bf16 v[30:33], v[164:167], v[206:209], v[30:33]
	v_mfma_f32_16x16x32_bf16 v[6:9], v[144:147], v[210:213], v[6:9]
	v_mfma_f32_16x16x32_bf16 v[6:9], v[148:151], v[214:217], v[6:9]
	v_mfma_f32_16x16x32_bf16 v[10:13], v[160:163], v[210:213], v[10:13]
	v_mfma_f32_16x16x32_bf16 v[10:13], v[164:167], v[214:217], v[10:13]
	v_mfma_f32_16x16x32_bf16 v[50:53], v[152:155], v[180:183], v[50:53]
	v_mfma_f32_16x16x32_bf16 v[50:53], v[156:159], v[184:187], v[50:53]
	v_mfma_f32_16x16x32_bf16 v[58:61], v[168:171], v[180:183], v[58:61]
	v_mfma_f32_16x16x32_bf16 v[58:61], v[172:175], v[184:187], v[58:61]
	v_mfma_f32_16x16x32_bf16 v[34:37], v[152:155], v[188:191], v[34:37]
	v_mfma_f32_16x16x32_bf16 v[34:37], v[156:159], v[192:195], v[34:37]
	v_mfma_f32_16x16x32_bf16 v[42:45], v[168:171], v[188:191], v[42:45]
	v_mfma_f32_16x16x32_bf16 v[42:45], v[172:175], v[192:195], v[42:45]
	v_mfma_f32_16x16x32_bf16 v[18:21], v[152:155], v[202:205], v[18:21]
	v_mfma_f32_16x16x32_bf16 v[18:21], v[156:159], v[206:209], v[18:21]
	v_mfma_f32_16x16x32_bf16 v[26:29], v[168:171], v[202:205], v[26:29]
	v_mfma_f32_16x16x32_bf16 v[26:29], v[172:175], v[206:209], v[26:29]
	v_mfma_f32_16x16x32_bf16 v[2:5], v[152:155], v[210:213], v[2:5]
	v_mfma_f32_16x16x32_bf16 v[2:5], v[156:159], v[214:217], v[2:5]
	v_mfma_f32_16x16x32_bf16 v[14:17], v[168:171], v[210:213], v[14:17]
	v_mfma_f32_16x16x32_bf16 v[14:17], v[172:175], v[214:217], v[14:17]
	s_setprio 0
	s_barrier
	s_add_i32 s85, s85, 2
	s_add_u32 s46, s46, 0x100
	s_addc_u32 s47, s47, 0
	s_add_u32 s83, s83, 0x100
	s_addc_u32 s84, s84, 0
	s_cmp_gt_u32 s85, 13
	s_cbranch_scc0 .LBB0_132
	s_and_b64 vcc, exec, s[10:11]
	s_cbranch_vccz .LBB0_135
	s_barrier

; #define PG8_STAGE(bufoff, gbase, voff) do { _Pragma("unroll") for (int _i = 0; _i < 2; ++_i) \
;         __builtin_amdgcn_global_load_lds((const unsigned*)((const char*)(gbase) + (voff)[_i]), (PG8_LAS unsigned*)(lds + (bufoff) + ldsw + _i * 8192), 16, 0, 0); } while (0)
; #define PG8_LDA(dst, b, h) do { _Pragma("unroll") for (int m = 0; m < 4; ++m) _Pragma("unroll") for (int k = 0; k < 2; ++k) dst[m][k] = *(const PG8_LAS bf16x8*)(lds + PG8_SA(b, h) + aoff + m * 2048 + k * 1024); } while (0)
; #define PG8_LDB(dst, b, h) do { _Pragma("unroll") for (int n = 0; n < 2; ++n) _Pragma("unroll") for (int k = 0; k < 2; ++k) dst[n][k] = *(const PG8_LAS bf16x8*)(lds + PG8_SB(b, h) + boff + n * 2048 + k * 1024); } while (0)
; #define PG8_MMA(ai, bj, At, Bt) do { __builtin_amdgcn_s_setprio(1); _Pragma("unroll") for (int m = 0; m < 4; ++m) _Pragma("unroll") for (int n = 0; n < 2; ++n) _Pragma("unroll") for (int k = 0; k < 2; ++k) \
;         acc[ai][bj][m][n] = __builtin_amdgcn_mfma_f32_16x16x32_bf16(Bt[n][k], At[m][k], acc[ai][bj][m][n], 0, 0, 0); __builtin_amdgcn_s_setprio(0); } while (0)
; #define PG8_WAIT_V(n) asm volatile("s_waitcnt vmcnt(" #n ")" ::: "memory")
; #define PG8_WAIT_L(n) asm volatile("s_waitcnt lgkmcnt(" #n ")" ::: "memory")
; template <class Epi, class Sched, bool ALIGN_EPI = false, bool SP2 = false>
; __device__ __forceinline__ void gemm_phase(PG8_LAS unsigned char* lds, const Gemm g, const Sched& S, const Epi& E) {
;     ...
;             const bool last = (t == nt - 2);
;             const char* a1 = cA + (size_t)(t + 1) * kstep;
;             const char* a2 = last ? nA : cA + (size_t)(t + 2) * kstep; const char* b2 = last ? nB : cB + (size_t)(t + 2) * kstep;
;             const char* a3 = a2 + kstep; const char* b3 = b2 + kstep;
;             if (last && has_next) S.a_ready(nxt);
;             if constexpr (SP2) {
;             PG8_LDB(B0, 0, 0); PG8_LDB(B1, 0, 1); PG8_SCHED; PG8_LDA(At, 0, 0); PG8_STAGE(PG8_SA(1, 1), a1 + hstep, voffA);
;             PG8_WAIT_V(8); PG8_WAIT_L(0); PG8_BAR; PG8_MMA(0, 0, At, B0); PG8_MMA(0, 1, At, B1); PG8_BAR; PG8_SCHED;
;             PG8_LDA(At, 0, 1); PG8_STAGE(PG8_SB(0, 0), b2, voffB); PG8_STAGE(PG8_SB(0, 1), b2 + hstep, voffB); PG8_STAGE(PG8_SA(0, 0), a2, voffA);
;             PG8_WAIT_V(8); PG8_WAIT_L(0); PG8_BAR; PG8_MMA(1, 0, At, B0); PG8_MMA(1, 1, At, B1); PG8_BAR; PG8_SCHED;
.LBB0_220:
	s_add_u32 s18, s60, 0xfffc0080
	s_addc_u32 s38, s61, -1
	s_add_i32 s39, 0, 0x10000
	s_cmp_eq_u32 s82, 12
	s_cselect_b32 s65, s47, s38
	s_cselect_b32 s64, s78, s18
	v_add_u32_e32 v145, s39, v141
	s_cselect_b32 s57, s49, s81
	s_cselect_b32 s56, s79, s80
	s_add_i32 s18, 0, 0x14000
	ds_read_b128 v[146:149], v145
	ds_read_b128 v[150:153], v145 offset:1024
	ds_read_b128 v[154:157], v145 offset:2048
	ds_read_b128 v[158:161], v145 offset:3072
	v_add_u32_e32 v145, s18, v141
	ds_read_b128 v[162:165], v145
	ds_read_b128 v[166:169], v145 offset:1024
	ds_read_b128 v[170:173], v145 offset:2048
	ds_read_b128 v[174:177], v145 offset:3072
	v_lshl_add_u64 v[194:195], s[60:61], 0, v[136:137]
	s_add_i32 m0, s29, 0xc000
	ds_read_b128 v[178:181], v144
	ds_read_b128 v[182:185], v144 offset:1024
	ds_read_b128 v[186:189], v144 offset:2048
	ds_read_b128 v[190:193], v144 offset:3072
	ds_read_b128 v[202:205], v144 offset:4096
	ds_read_b128 v[206:209], v144 offset:5120
	ds_read_b128 v[210:213], v144 offset:6144
	ds_read_b128 v[214:217], v144 offset:7168
	global_load_lds_dwordx4 v[194:195], off
	v_lshl_add_u64 v[194:195], s[60:61], 0, v[138:139]
	s_add_i32 m0, s29, 0xe000
	s_nop 0
	global_load_lds_dwordx4 v[194:195], off
	s_waitcnt vmcnt(8)
	s_waitcnt lgkmcnt(0)
	s_barrier
	s_setprio 1
	s_waitcnt lgkmcnt(0)
	v_mfma_f32_16x16x32_bf16 v[114:117], v[146:149], v[178:181], v[114:117]
	v_mfma_f32_16x16x32_bf16 v[114:117], v[150:153], v[182:185], v[114:117]
	v_mfma_f32_16x16x32_bf16 v[122:125], v[162:165], v[178:181], v[122:125]
	v_mfma_f32_16x16x32_bf16 v[122:125], v[166:169], v[182:185], v[122:125]
	v_mfma_f32_16x16x32_bf16 v[98:101], v[146:149], v[186:189], v[98:101]
	v_mfma_f32_16x16x32_bf16 v[98:101], v[150:153], v[190:193], v[98:101]
	v_mfma_f32_16x16x32_bf16 v[106:109], v[162:165], v[186:189], v[106:109]
	v_mfma_f32_16x16x32_bf16 v[106:109], v[166:169], v[190:193], v[106:109]
	v_mfma_f32_16x16x32_bf16 v[82:85], v[146:149], v[202:205], v[82:85]
	v_mfma_f32_16x16x32_bf16 v[82:85], v[150:153], v[206:209], v[82:85]
	v_mfma_f32_16x16x32_bf16 v[90:93], v[162:165], v[202:205], v[90:93]
	v_mfma_f32_16x16x32_bf16 v[90:93], v[166:169], v[206:209], v[90:93]
	v_mfma_f32_16x16x32_bf16 v[66:69], v[146:149], v[210:213], v[66:69]
	v_mfma_f32_16x16x32_bf16 v[66:69], v[150:153], v[214:217], v[66:69]
	v_mfma_f32_16x16x32_bf16 v[74:77], v[162:165], v[210:213], v[74:77]
	v_mfma_f32_16x16x32_bf16 v[74:77], v[166:169], v[214:217], v[74:77]
	v_mfma_f32_16x16x32_bf16 v[118:121], v[154:157], v[178:181], v[118:121]
	v_mfma_f32_16x16x32_bf16 v[118:121], v[158:161], v[182:185], v[118:121]
	v_mfma_f32_16x16x32_bf16 v[126:129], v[170:173], v[178:181], v[126:129]
	v_mfma_f32_16x16x32_bf16 v[126:129], v[174:177], v[182:185], v[126:129]
	v_mfma_f32_16x16x32_bf16 v[102:105], v[154:157], v[186:189], v[102:105]
	v_mfma_f32_16x16x32_bf16 v[102:105], v[158:161], v[190:193], v[102:105]
	v_mfma_f32_16x16x32_bf16 v[110:113], v[170:173], v[186:189], v[110:113]
	v_mfma_f32_16x16x32_bf16 v[110:113], v[174:177], v[190:193], v[110:113]
	v_mfma_f32_16x16x32_bf16 v[86:89], v[154:157], v[202:205], v[86:89]
	v_mfma_f32_16x16x32_bf16 v[86:89], v[158:161], v[206:209], v[86:89]
	v_mfma_f32_16x16x32_bf16 v[94:97], v[170:173], v[202:205], v[94:97]
	v_mfma_f32_16x16x32_bf16 v[94:97], v[174:177], v[206:209], v[94:97]
	v_mfma_f32_16x16x32_bf16 v[70:73], v[154:157], v[210:213], v[70:73]
	v_mfma_f32_16x16x32_bf16 v[70:73], v[158:161], v[214:217], v[70:73]
	v_mfma_f32_16x16x32_bf16 v[78:81], v[170:173], v[210:213], v[78:81]
	v_mfma_f32_16x16x32_bf16 v[78:81], v[174:177], v[214:217], v[78:81]
	s_setprio 0
	s_barrier
	s_add_i32 s38, s39, s27
	v_lshl_add_u64 v[194:195], s[56:57], 0, v[0:1]
	s_mov_b32 m0, s38
	ds_read_b128 v[178:181], v144 offset:16384
	ds_read_b128 v[182:185], v144 offset:17408
	ds_read_b128 v[186:189], v144 offset:18432
	ds_read_b128 v[190:193], v144 offset:19456
	ds_read_b128 v[202:205], v144 offset:20480
	ds_read_b128 v[206:209], v144 offset:21504
	ds_read_b128 v[210:213], v144 offset:22528
	ds_read_b128 v[214:217], v144 offset:23552
	global_load_lds_dwordx4 v[194:195], off
	s_add_i32 m0, s38, 0x2000
	s_add_u32 s38, s56, 0x40000
	v_lshl_add_u64 v[218:219], s[56:57], 0, v[130:131]
	s_addc_u32 s39, s57, 0
	s_add_i32 s18, s18, s27
	global_load_lds_dwordx4 v[218:219], off
	v_lshl_add_u64 v[220:221], s[38:39], 0, v[0:1]
	s_mov_b32 m0, s18
	v_lshl_add_u64 v[222:223], s[64:65], 0, v[132:133]
	global_load_lds_dwordx4 v[220:221], off
	v_lshl_add_u64 v[220:221], s[38:39], 0, v[130:131]
	s_add_i32 m0, s18, 0x2000
	s_nop 0
	global_load_lds_dwordx4 v[220:221], off
	v_lshl_add_u64 v[220:221], s[64:65], 0, v[134:135]
	s_mov_b32 m0, s29
	s_nop 0
	global_load_lds_dwordx4 v[220:221], off
	s_mov_b32 m0, s33
	s_nop 0
	global_load_lds_dwordx4 v[222:223], off
	s_waitcnt vmcnt(8)
	s_waitcnt lgkmcnt(0)
	s_barrier
; #define PG8_STAGE(bufoff, gbase, voff) do { _Pragma("unroll") for (int _i = 0; _i < 2; ++_i) \
;         __builtin_amdgcn_global_load_lds((const unsigned*)((const char*)(gbase) + (voff)[_i]), (PG8_LAS unsigned*)(lds + (bufoff) + ldsw + _i * 8192), 16, 0, 0); } while (0)
; #define PG8_LDA(dst, b, h) do { _Pragma("unroll") for (int m = 0; m < 4; ++m) _Pragma("unroll") for (int k = 0; k < 2; ++k) dst[m][k] = *(const PG8_LAS bf16x8*)(lds + PG8_SA(b, h) + aoff + m * 2048 + k * 1024); } while (0)
; #define PG8_LDB(dst, b, h) do { _Pragma("unroll") for (int n = 0; n < 2; ++n) _Pragma("unroll") for (int k = 0; k < 2; ++k) dst[n][k] = *(const PG8_LAS bf16x8*)(lds + PG8_SB(b, h) + boff + n * 2048 + k * 1024); } while (0)
; #define PG8_MMA(ai, bj, At, Bt) do { __builtin_amdgcn_s_setprio(1); _Pragma("unroll") for (int m = 0; m < 4; ++m) _Pragma("unroll") for (int n = 0; n < 2; ++n) _Pragma("unroll") for (int k = 0; k < 2; ++k) \
;         acc[ai][bj][m][n] = __builtin_amdgcn_mfma_f32_16x16x32_bf16(Bt[n][k], At[m][k], acc[ai][bj][m][n], 0, 0, 0); __builtin_amdgcn_s_setprio(0); } while (0)
; #define PG8_WAIT_V(n) asm volatile("s_waitcnt vmcnt(" #n ")" ::: "memory")
; #define PG8_WAIT_L(n) asm volatile("s_waitcnt lgkmcnt(" #n ")" ::: "memory")
; #define PG8_BAR __builtin_amdgcn_s_barrier()
; #define PG8_SCHED __builtin_amdgcn_sched_barrier(0)
; template <class Epi, class Sched, bool ALIGN_EPI = false, bool SP2 = false>
; __device__ __forceinline__ void gemm_phase(PG8_LAS unsigned char* lds, const Gemm g, const Sched& S, const Epi& E) {
;     ...
;             PG8_WAIT_V(8); PG8_WAIT_L(0); PG8_BAR; PG8_MMA(1, 0, At, B0); PG8_MMA(1, 1, At, B1); PG8_BAR; PG8_SCHED;
;             PG8_LDB(B0, 1, 0); PG8_LDB(B1, 1, 1); PG8_SCHED; PG8_LDA(At, 1, 0); PG8_STAGE(PG8_SA(0, 1), a2 + hstep, voffA);
;             PG8_WAIT_V(8); PG8_WAIT_L(0); PG8_BAR; PG8_MMA(0, 0, At, B0); PG8_MMA(0, 1, At, B1); PG8_BAR; PG8_SCHED;
	s_setprio 1
	s_waitcnt lgkmcnt(0)
	v_mfma_f32_16x16x32_bf16 v[50:53], v[146:149], v[178:181], v[50:53]
	v_mfma_f32_16x16x32_bf16 v[50:53], v[150:153], v[182:185], v[50:53]
	v_mfma_f32_16x16x32_bf16 v[58:61], v[162:165], v[178:181], v[58:61]
	v_mfma_f32_16x16x32_bf16 v[58:61], v[166:169], v[182:185], v[58:61]
	v_mfma_f32_16x16x32_bf16 v[34:37], v[146:149], v[186:189], v[34:37]
	v_mfma_f32_16x16x32_bf16 v[34:37], v[150:153], v[190:193], v[34:37]
	v_mfma_f32_16x16x32_bf16 v[42:45], v[162:165], v[186:189], v[42:45]
	v_mfma_f32_16x16x32_bf16 v[42:45], v[166:169], v[190:193], v[42:45]
	v_mfma_f32_16x16x32_bf16 v[18:21], v[146:149], v[202:205], v[18:21]
	v_mfma_f32_16x16x32_bf16 v[18:21], v[150:153], v[206:209], v[18:21]
	v_mfma_f32_16x16x32_bf16 v[26:29], v[162:165], v[202:205], v[26:29]
	v_mfma_f32_16x16x32_bf16 v[26:29], v[166:169], v[206:209], v[26:29]
	v_mfma_f32_16x16x32_bf16 v[2:5], v[146:149], v[210:213], v[2:5]
	v_mfma_f32_16x16x32_bf16 v[2:5], v[150:153], v[214:217], v[2:5]
	v_mfma_f32_16x16x32_bf16 v[10:13], v[162:165], v[210:213], v[10:13]
	v_mfma_f32_16x16x32_bf16 v[10:13], v[166:169], v[214:217], v[10:13]
	v_mfma_f32_16x16x32_bf16 v[54:57], v[154:157], v[178:181], v[54:57]
	v_mfma_f32_16x16x32_bf16 v[54:57], v[158:161], v[182:185], v[54:57]
	v_mfma_f32_16x16x32_bf16 v[62:65], v[170:173], v[178:181], v[62:65]
	v_mfma_f32_16x16x32_bf16 v[62:65], v[174:177], v[182:185], v[62:65]
	v_mfma_f32_16x16x32_bf16 v[38:41], v[154:157], v[186:189], v[38:41]
	v_mfma_f32_16x16x32_bf16 v[38:41], v[158:161], v[190:193], v[38:41]
	v_mfma_f32_16x16x32_bf16 v[46:49], v[170:173], v[186:189], v[46:49]
	v_mfma_f32_16x16x32_bf16 v[46:49], v[174:177], v[190:193], v[46:49]
	v_mfma_f32_16x16x32_bf16 v[22:25], v[154:157], v[202:205], v[22:25]
	v_mfma_f32_16x16x32_bf16 v[22:25], v[158:161], v[206:209], v[22:25]
	v_mfma_f32_16x16x32_bf16 v[30:33], v[170:173], v[202:205], v[30:33]
	v_mfma_f32_16x16x32_bf16 v[30:33], v[174:177], v[206:209], v[30:33]
	v_mfma_f32_16x16x32_bf16 v[6:9], v[154:157], v[210:213], v[6:9]
	v_mfma_f32_16x16x32_bf16 v[6:9], v[158:161], v[214:217], v[6:9]
	v_mfma_f32_16x16x32_bf16 v[14:17], v[170:173], v[210:213], v[14:17]
	v_mfma_f32_16x16x32_bf16 v[14:17], v[174:177], v[214:217], v[14:17]
	s_setprio 0
	s_barrier
	s_add_i32 s18, 0, 0x18000
	v_add_u32_e32 v145, s18, v141
	s_add_i32 s83, 0, 0x1c000
	ds_read_b128 v[146:149], v145
	ds_read_b128 v[150:153], v145 offset:1024
	ds_read_b128 v[154:157], v145 offset:2048
	ds_read_b128 v[158:161], v145 offset:3072
	v_add_u32_e32 v145, s83, v141
	ds_read_b128 v[162:165], v145
	ds_read_b128 v[166:169], v145 offset:1024
	ds_read_b128 v[170:173], v145 offset:2048
	ds_read_b128 v[174:177], v145 offset:3072
	s_add_u32 s38, s64, 0x40000
	s_addc_u32 s39, s65, 0
	s_mov_b32 m0, s58
	v_lshl_add_u64 v[224:225], s[38:39], 0, v[134:135]
	ds_read_b128 v[178:181], v144 offset:32768
	ds_read_b128 v[182:185], v144 offset:33792
	ds_read_b128 v[186:189], v144 offset:34816
	ds_read_b128 v[190:193], v144 offset:35840
	ds_read_b128 v[202:205], v144 offset:36864
	ds_read_b128 v[206:209], v144 offset:37888
	ds_read_b128 v[210:213], v144 offset:38912
	ds_read_b128 v[214:217], v144 offset:39936
	global_load_lds_dwordx4 v[224:225], off
	v_lshl_add_u64 v[224:225], s[38:39], 0, v[132:133]
	s_mov_b32 m0, s69
	s_nop 0
	global_load_lds_dwordx4 v[224:225], off
	s_waitcnt vmcnt(8)
	s_waitcnt lgkmcnt(0)
	s_barrier
	s_setprio 1
	s_waitcnt lgkmcnt(0)
	v_mfma_f32_16x16x32_bf16 v[114:117], v[146:149], v[178:181], v[114:117]
	v_mfma_f32_16x16x32_bf16 v[114:117], v[150:153], v[182:185], v[114:117]
	v_mfma_f32_16x16x32_bf16 v[122:125], v[162:165], v[178:181], v[122:125]
	v_mfma_f32_16x16x32_bf16 v[122:125], v[166:169], v[182:185], v[122:125]
	v_mfma_f32_16x16x32_bf16 v[98:101], v[146:149], v[186:189], v[98:101]
	v_mfma_f32_16x16x32_bf16 v[98:101], v[150:153], v[190:193], v[98:101]
	v_mfma_f32_16x16x32_bf16 v[106:109], v[162:165], v[186:189], v[106:109]
	v_mfma_f32_16x16x32_bf16 v[106:109], v[166:169], v[190:193], v[106:109]
	v_mfma_f32_16x16x32_bf16 v[82:85], v[146:149], v[202:205], v[82:85]
	v_mfma_f32_16x16x32_bf16 v[82:85], v[150:153], v[206:209], v[82:85]
	v_mfma_f32_16x16x32_bf16 v[90:93], v[162:165], v[202:205], v[90:93]
	v_mfma_f32_16x16x32_bf16 v[90:93], v[166:169], v[206:209], v[90:93]
	v_mfma_f32_16x16x32_bf16 v[66:69], v[146:149], v[210:213], v[66:69]
	v_mfma_f32_16x16x32_bf16 v[66:69], v[150:153], v[214:217], v[66:69]
	v_mfma_f32_16x16x32_bf16 v[74:77], v[162:165], v[210:213], v[74:77]
	v_mfma_f32_16x16x32_bf16 v[74:77], v[166:169], v[214:217], v[74:77]
	v_mfma_f32_16x16x32_bf16 v[118:121], v[154:157], v[178:181], v[118:121]
	v_mfma_f32_16x16x32_bf16 v[118:121], v[158:161], v[182:185], v[118:121]
	v_mfma_f32_16x16x32_bf16 v[126:129], v[170:173], v[178:181], v[126:129]
	v_mfma_f32_16x16x32_bf16 v[126:129], v[174:177], v[182:185], v[126:129]
	v_mfma_f32_16x16x32_bf16 v[102:105], v[154:157], v[186:189], v[102:105]
	v_mfma_f32_16x16x32_bf16 v[102:105], v[158:161], v[190:193], v[102:105]
	v_mfma_f32_16x16x32_bf16 v[110:113], v[170:173], v[186:189], v[110:113]
	v_mfma_f32_16x16x32_bf16 v[110:113], v[174:177], v[190:193], v[110:113]
	v_mfma_f32_16x16x32_bf16 v[86:89], v[154:157], v[202:205], v[86:89]
	v_mfma_f32_16x16x32_bf16 v[86:89], v[158:161], v[206:209], v[86:89]
	v_mfma_f32_16x16x32_bf16 v[94:97], v[170:173], v[202:205], v[94:97]
	v_mfma_f32_16x16x32_bf16 v[94:97], v[174:177], v[206:209], v[94:97]
	v_mfma_f32_16x16x32_bf16 v[70:73], v[154:157], v[210:213], v[70:73]
	v_mfma_f32_16x16x32_bf16 v[70:73], v[158:161], v[214:217], v[70:73]
	v_mfma_f32_16x16x32_bf16 v[78:81], v[170:173], v[210:213], v[78:81]
	v_mfma_f32_16x16x32_bf16 v[78:81], v[174:177], v[214:217], v[78:81]
	s_setprio 0
	s_barrier
; #define PG8_STAGE(bufoff, gbase, voff) do { _Pragma("unroll") for (int _i = 0; _i < 2; ++_i) \
;         __builtin_amdgcn_global_load_lds((const unsigned*)((const char*)(gbase) + (voff)[_i]), (PG8_LAS unsigned*)(lds + (bufoff) + ldsw + _i * 8192), 16, 0, 0); } while (0)
; #define PG8_LDA(dst, b, h) do { _Pragma("unroll") for (int m = 0; m < 4; ++m) _Pragma("unroll") for (int k = 0; k < 2; ++k) dst[m][k] = *(const PG8_LAS bf16x8*)(lds + PG8_SA(b, h) + aoff + m * 2048 + k * 1024); } while (0)
; #define PG8_MMA(ai, bj, At, Bt) do { __builtin_amdgcn_s_setprio(1); _Pragma("unroll") for (int m = 0; m < 4; ++m) _Pragma("unroll") for (int n = 0; n < 2; ++n) _Pragma("unroll") for (int k = 0; k < 2; ++k) \
;         acc[ai][bj][m][n] = __builtin_amdgcn_mfma_f32_16x16x32_bf16(Bt[n][k], At[m][k], acc[ai][bj][m][n], 0, 0, 0); __builtin_amdgcn_s_setprio(0); } while (0)
; #define PG8_WAIT_V(n) asm volatile("s_waitcnt vmcnt(" #n ")" ::: "memory")
; #define PG8_WAIT_L(n) asm volatile("s_waitcnt lgkmcnt(" #n ")" ::: "memory")
; #define PG8_BAR __builtin_amdgcn_s_barrier()
; #define PG8_SCHED __builtin_amdgcn_sched_barrier(0)
; template <class Epi, class Sched, bool ALIGN_EPI = false, bool SP2 = false>
; __device__ __forceinline__ void gemm_phase(PG8_LAS unsigned char* lds, const Gemm g, const Sched& S, const Epi& E) {
;     ...
;             PG8_LDA(At, 1, 1); PG8_STAGE(PG8_SB(1, 0), b3, voffB); PG8_STAGE(PG8_SB(1, 1), b3 + hstep, voffB); PG8_STAGE(PG8_SA(1, 0), a3, voffA);
;             PG8_WAIT_V(8); PG8_WAIT_L(0); PG8_BAR; PG8_MMA(1, 0, At, B0); PG8_MMA(1, 1, At, B1); PG8_BAR; PG8_SCHED;
	s_add_i32 s18, s18, s27
	v_lshl_add_u64 v[194:195], v[194:195], 0, s[30:31]
	s_mov_b32 m0, s18
	ds_read_b128 v[178:181], v144 offset:49152
	ds_read_b128 v[182:185], v144 offset:50176
	ds_read_b128 v[186:189], v144 offset:51200
	ds_read_b128 v[190:193], v144 offset:52224
	ds_read_b128 v[202:205], v144 offset:53248
	ds_read_b128 v[206:209], v144 offset:54272
	ds_read_b128 v[210:213], v144 offset:55296
	ds_read_b128 v[214:217], v144 offset:56320
	global_load_lds_dwordx4 v[194:195], off
	s_add_i32 m0, s18, 0x2000
	s_add_u32 s38, s56, 0x40080
	v_lshl_add_u64 v[194:195], v[218:219], 0, s[30:31]
	s_addc_u32 s39, s57, 0
	s_add_i32 s18, s83, s27
	global_load_lds_dwordx4 v[194:195], off
	v_lshl_add_u64 v[194:195], s[38:39], 0, v[0:1]
	s_mov_b32 m0, s18
	s_nop 0
	global_load_lds_dwordx4 v[194:195], off
	v_lshl_add_u64 v[194:195], s[38:39], 0, v[130:131]
	s_add_i32 m0, s18, 0x2000
	s_nop 0
	global_load_lds_dwordx4 v[194:195], off
	v_lshl_add_u64 v[194:195], v[220:221], 0, s[30:31]
	s_mov_b32 m0, s71
	s_nop 0
	global_load_lds_dwordx4 v[194:195], off
	v_lshl_add_u64 v[194:195], v[222:223], 0, s[30:31]
	s_mov_b32 m0, s72
	s_nop 0
	global_load_lds_dwordx4 v[194:195], off
	s_waitcnt vmcnt(8)
	s_waitcnt lgkmcnt(0)
	s_barrier
	s_setprio 1
	s_waitcnt lgkmcnt(0)
	v_mfma_f32_16x16x32_bf16 v[50:53], v[146:149], v[178:181], v[50:53]
	v_mfma_f32_16x16x32_bf16 v[50:53], v[150:153], v[182:185], v[50:53]
	v_mfma_f32_16x16x32_bf16 v[58:61], v[162:165], v[178:181], v[58:61]
	v_mfma_f32_16x16x32_bf16 v[58:61], v[166:169], v[182:185], v[58:61]
	v_mfma_f32_16x16x32_bf16 v[34:37], v[146:149], v[186:189], v[34:37]
	v_mfma_f32_16x16x32_bf16 v[34:37], v[150:153], v[190:193], v[34:37]
	v_mfma_f32_16x16x32_bf16 v[42:45], v[162:165], v[186:189], v[42:45]
	v_mfma_f32_16x16x32_bf16 v[42:45], v[166:169], v[190:193], v[42:45]
	v_mfma_f32_16x16x32_bf16 v[18:21], v[146:149], v[202:205], v[18:21]
	v_mfma_f32_16x16x32_bf16 v[18:21], v[150:153], v[206:209], v[18:21]
	v_mfma_f32_16x16x32_bf16 v[26:29], v[162:165], v[202:205], v[26:29]
	v_mfma_f32_16x16x32_bf16 v[26:29], v[166:169], v[206:209], v[26:29]
	v_mfma_f32_16x16x32_bf16 v[2:5], v[146:149], v[210:213], v[2:5]
	v_mfma_f32_16x16x32_bf16 v[2:5], v[150:153], v[214:217], v[2:5]
	v_mfma_f32_16x16x32_bf16 v[10:13], v[162:165], v[210:213], v[10:13]
	v_mfma_f32_16x16x32_bf16 v[10:13], v[166:169], v[214:217], v[10:13]
	v_mfma_f32_16x16x32_bf16 v[54:57], v[154:157], v[178:181], v[54:57]
	v_mfma_f32_16x16x32_bf16 v[54:57], v[158:161], v[182:185], v[54:57]
	v_mfma_f32_16x16x32_bf16 v[62:65], v[170:173], v[178:181], v[62:65]
	v_mfma_f32_16x16x32_bf16 v[62:65], v[174:177], v[182:185], v[62:65]
	v_mfma_f32_16x16x32_bf16 v[38:41], v[154:157], v[186:189], v[38:41]
	v_mfma_f32_16x16x32_bf16 v[38:41], v[158:161], v[190:193], v[38:41]
	v_mfma_f32_16x16x32_bf16 v[46:49], v[170:173], v[186:189], v[46:49]
	v_mfma_f32_16x16x32_bf16 v[46:49], v[174:177], v[190:193], v[46:49]
	v_mfma_f32_16x16x32_bf16 v[22:25], v[154:157], v[202:205], v[22:25]
	v_mfma_f32_16x16x32_bf16 v[22:25], v[158:161], v[206:209], v[22:25]
	v_mfma_f32_16x16x32_bf16 v[30:33], v[170:173], v[202:205], v[30:33]
	v_mfma_f32_16x16x32_bf16 v[30:33], v[174:177], v[206:209], v[30:33]
	v_mfma_f32_16x16x32_bf16 v[6:9], v[154:157], v[210:213], v[6:9]
	v_mfma_f32_16x16x32_bf16 v[6:9], v[158:161], v[214:217], v[6:9]
	v_mfma_f32_16x16x32_bf16 v[14:17], v[170:173], v[210:213], v[14:17]
	v_mfma_f32_16x16x32_bf16 v[14:17], v[174:177], v[214:217], v[14:17]
	s_setprio 0
	s_barrier
	s_add_i32 s82, s82, 2
	s_add_u32 s60, s60, 0x100
	s_addc_u32 s61, s61, 0
	s_add_u32 s80, s80, 0x100
	s_addc_u32 s81, s81, 0
	s_cmp_gt_u32 s82, 13
	s_cbranch_scc0 .LBB0_220
	s_and_b64 vcc, exec, s[44:45]
	s_cbranch_vccz .LBB0_223
	s_barrier

; #define PG8_STAGE(bufoff, gbase, voff) do { _Pragma("unroll") for (int _i = 0; _i < 2; ++_i) \
;         __builtin_amdgcn_global_load_lds((const unsigned*)((const char*)(gbase) + (voff)[_i]), (PG8_LAS unsigned*)(lds + (bufoff) + ldsw + _i * 8192), 16, 0, 0); } while (0)
; #define PG8_LDA(dst, b, h) do { _Pragma("unroll") for (int m = 0; m < 4; ++m) _Pragma("unroll") for (int k = 0; k < 2; ++k) dst[m][k] = *(const PG8_LAS bf16x8*)(lds + PG8_SA(b, h) + aoff + m * 2048 + k * 1024); } while (0)
; #define PG8_LDB(dst, b, h) do { _Pragma("unroll") for (int n = 0; n < 2; ++n) _Pragma("unroll") for (int k = 0; k < 2; ++k) dst[n][k] = *(const PG8_LAS bf16x8*)(lds + PG8_SB(b, h) + boff + n * 2048 + k * 1024); } while (0)
; #define PG8_MMA(ai, bj, At, Bt) do { __builtin_amdgcn_s_setprio(1); _Pragma("unroll") for (int m = 0; m < 4; ++m) _Pragma("unroll") for (int n = 0; n < 2; ++n) _Pragma("unroll") for (int k = 0; k < 2; ++k) \
;         acc[ai][bj][m][n] = __builtin_amdgcn_mfma_f32_16x16x32_bf16(Bt[n][k], At[m][k], acc[ai][bj][m][n], 0, 0, 0); __builtin_amdgcn_s_setprio(0); } while (0)
; #define PG8_WAIT_V(n) asm volatile("s_waitcnt vmcnt(" #n ")" ::: "memory")
; #define PG8_WAIT_L(n) asm volatile("s_waitcnt lgkmcnt(" #n ")" ::: "memory")
; template <class Epi, class Sched, bool ALIGN_EPI = false, bool SP2 = false>
; __device__ __forceinline__ void gemm_phase(PG8_LAS unsigned char* lds, const Gemm g, const Sched& S, const Epi& E) {
;     ...
;             const bool last = (t == nt - 2);
;             const char* a1 = cA + (size_t)(t + 1) * kstep;
;             const char* a2 = last ? nA : cA + (size_t)(t + 2) * kstep; const char* b2 = last ? nB : cB + (size_t)(t + 2) * kstep;
;             const char* a3 = a2 + kstep; const char* b3 = b2 + kstep;
;             if (last && has_next) S.a_ready(nxt);
;             if constexpr (SP2) {
;             PG8_LDB(B0, 0, 0); PG8_LDB(B1, 0, 1); PG8_SCHED; PG8_LDA(At, 0, 0); PG8_STAGE(PG8_SA(1, 1), a1 + hstep, voffA);
;             PG8_WAIT_V(8); PG8_WAIT_L(0); PG8_BAR; PG8_MMA(0, 0, At, B0); PG8_MMA(0, 1, At, B1); PG8_BAR; PG8_SCHED;
;             PG8_LDA(At, 0, 1); PG8_STAGE(PG8_SB(0, 0), b2, voffB); PG8_STAGE(PG8_SB(0, 1), b2 + hstep, voffB); PG8_STAGE(PG8_SA(0, 0), a2, voffA);
;             PG8_WAIT_V(8); PG8_WAIT_L(0); PG8_BAR; PG8_MMA(1, 0, At, B0); PG8_MMA(1, 1, At, B1); PG8_BAR; PG8_SCHED;
.LBB0_274:
	s_add_i32 vcc_lo, s46, 2
	s_add_u32 s38, s48, 0x80
	s_addc_u32 s39, s49, 0
	s_add_i32 vcc_hi, 0, 0x10000
	s_cmp_eq_u32 s99, s46
	s_cselect_b32 s47, s81, s39
	s_cselect_b32 s46, s80, s38
	s_cselect_b32 s39, s83, s51
	s_cselect_b32 s38, s82, s50
	s_add_i32 s18, 0, 0x14000
	v_add_u32_e32 v142, vcc_hi, v245
	v_add_u32_e32 v158, s18, v245
	ds_read_b128 v[110:113], v142
	ds_read_b128 v[118:121], v142 offset:1024
	ds_read_b128 v[138:141], v142 offset:2048
	ds_read_b128 v[142:145], v142 offset:3072
	ds_read_b128 v[146:149], v158
	ds_read_b128 v[150:153], v158 offset:1024
	ds_read_b128 v[154:157], v158 offset:2048
	ds_read_b128 v[158:161], v158 offset:3072
	v_lshl_add_u64 v[210:211], s[48:49], 0, v[206:207]
	s_add_i32 m0, s92, 0xc000
	ds_read_b128 v[162:165], v247
	ds_read_b128 v[166:169], v247 offset:1024
	ds_read_b128 v[170:173], v247 offset:2048
	ds_read_b128 v[174:177], v247 offset:3072
	ds_read_b128 v[178:181], v247 offset:4096
	ds_read_b128 v[182:185], v247 offset:5120
	ds_read_b128 v[186:189], v247 offset:6144
	ds_read_b128 v[190:193], v247 offset:7168
	global_load_lds_dwordx4 v[210:211], off
	v_lshl_add_u64 v[210:211], s[48:49], 0, v[208:209]
	s_add_i32 m0, s92, 0xe000
	s_nop 0
	global_load_lds_dwordx4 v[210:211], off
	s_waitcnt vmcnt(8)
	s_waitcnt lgkmcnt(0)
	s_barrier
	s_setprio 1
	s_waitcnt lgkmcnt(0)
	v_mfma_f32_16x16x32_bf16 v[130:133], v[110:113], v[162:165], v[130:133]
	v_mfma_f32_16x16x32_bf16 v[130:133], v[118:121], v[166:169], v[130:133]
	v_mfma_f32_16x16x32_bf16 v[126:129], v[146:149], v[162:165], v[126:129]
	v_mfma_f32_16x16x32_bf16 v[126:129], v[150:153], v[166:169], v[126:129]
	v_mfma_f32_16x16x32_bf16 v[114:117], v[110:113], v[170:173], v[114:117]
	v_mfma_f32_16x16x32_bf16 v[114:117], v[118:121], v[174:177], v[114:117]
	v_mfma_f32_16x16x32_bf16 v[102:105], v[146:149], v[170:173], v[102:105]
	v_mfma_f32_16x16x32_bf16 v[102:105], v[150:153], v[174:177], v[102:105]
	v_mfma_f32_16x16x32_bf16 v[94:97], v[110:113], v[178:181], v[94:97]
	v_mfma_f32_16x16x32_bf16 v[94:97], v[118:121], v[182:185], v[94:97]
	v_mfma_f32_16x16x32_bf16 v[86:89], v[146:149], v[178:181], v[86:89]
	v_mfma_f32_16x16x32_bf16 v[86:89], v[150:153], v[182:185], v[86:89]
	v_mfma_f32_16x16x32_bf16 v[78:81], v[110:113], v[186:189], v[78:81]
	v_mfma_f32_16x16x32_bf16 v[78:81], v[118:121], v[190:193], v[78:81]
	v_mfma_f32_16x16x32_bf16 v[70:73], v[146:149], v[186:189], v[70:73]
	v_mfma_f32_16x16x32_bf16 v[70:73], v[150:153], v[190:193], v[70:73]
	v_mfma_f32_16x16x32_bf16 v[134:137], v[138:141], v[162:165], v[134:137]
	v_mfma_f32_16x16x32_bf16 v[134:137], v[142:145], v[166:169], v[134:137]
	v_mfma_f32_16x16x32_bf16 v[122:125], v[154:157], v[162:165], v[122:125]
	v_mfma_f32_16x16x32_bf16 v[122:125], v[158:161], v[166:169], v[122:125]
	v_mfma_f32_16x16x32_bf16 v[106:109], v[138:141], v[170:173], v[106:109]
	v_mfma_f32_16x16x32_bf16 v[106:109], v[142:145], v[174:177], v[106:109]
	v_mfma_f32_16x16x32_bf16 v[98:101], v[154:157], v[170:173], v[98:101]
	v_mfma_f32_16x16x32_bf16 v[98:101], v[158:161], v[174:177], v[98:101]
	v_mfma_f32_16x16x32_bf16 v[90:93], v[138:141], v[178:181], v[90:93]
	v_mfma_f32_16x16x32_bf16 v[90:93], v[142:145], v[182:185], v[90:93]
	v_mfma_f32_16x16x32_bf16 v[82:85], v[154:157], v[178:181], v[82:85]
	v_mfma_f32_16x16x32_bf16 v[82:85], v[158:161], v[182:185], v[82:85]
	v_mfma_f32_16x16x32_bf16 v[74:77], v[138:141], v[186:189], v[74:77]
	v_mfma_f32_16x16x32_bf16 v[74:77], v[142:145], v[190:193], v[74:77]
	v_mfma_f32_16x16x32_bf16 v[66:69], v[154:157], v[186:189], v[66:69]
	v_mfma_f32_16x16x32_bf16 v[66:69], v[158:161], v[190:193], v[66:69]
	s_setprio 0
	s_barrier
	s_add_i32 vcc_hi, vcc_hi, s6
	v_lshl_add_u64 v[210:211], s[38:39], 0, v[0:1]
	s_mov_b32 m0, vcc_hi
	ds_read_b128 v[162:165], v247 offset:16384
	ds_read_b128 v[166:169], v247 offset:17408
	ds_read_b128 v[170:173], v247 offset:18432
	ds_read_b128 v[174:177], v247 offset:19456
	ds_read_b128 v[178:181], v247 offset:20480
	ds_read_b128 v[182:185], v247 offset:21504
	ds_read_b128 v[186:189], v247 offset:22528
	ds_read_b128 v[190:193], v247 offset:23552
	global_load_lds_dwordx4 v[210:211], off
	s_add_i32 m0, vcc_hi, 0x2000
	v_lshl_add_u64 v[212:213], s[38:39], 0, v[204:205]
	s_add_u32 s38, s38, s58
	s_addc_u32 s39, s39, 0
	s_add_i32 s18, s18, s6
	global_load_lds_dwordx4 v[212:213], off
	v_lshl_add_u64 v[214:215], s[38:39], 0, v[0:1]
	s_mov_b32 m0, s18
	v_lshl_add_u64 v[216:217], s[38:39], 0, v[204:205]
	global_load_lds_dwordx4 v[214:215], off
	s_add_i32 m0, s18, 0x2000
	v_lshl_add_u64 v[218:219], s[46:47], 0, v[194:195]
	global_load_lds_dwordx4 v[216:217], off
	s_mov_b32 m0, s92
	v_lshl_add_u64 v[220:221], s[46:47], 0, v[202:203]
	global_load_lds_dwordx4 v[218:219], off
	s_mov_b32 m0, s93
	s_nop 0
	global_load_lds_dwordx4 v[220:221], off
	s_waitcnt vmcnt(8)
	s_waitcnt lgkmcnt(0)
	s_barrier
; #define PG8_STAGE(bufoff, gbase, voff) do { _Pragma("unroll") for (int _i = 0; _i < 2; ++_i) \
;         __builtin_amdgcn_global_load_lds((const unsigned*)((const char*)(gbase) + (voff)[_i]), (PG8_LAS unsigned*)(lds + (bufoff) + ldsw + _i * 8192), 16, 0, 0); } while (0)
; #define PG8_LDA(dst, b, h) do { _Pragma("unroll") for (int m = 0; m < 4; ++m) _Pragma("unroll") for (int k = 0; k < 2; ++k) dst[m][k] = *(const PG8_LAS bf16x8*)(lds + PG8_SA(b, h) + aoff + m * 2048 + k * 1024); } while (0)
; #define PG8_LDB(dst, b, h) do { _Pragma("unroll") for (int n = 0; n < 2; ++n) _Pragma("unroll") for (int k = 0; k < 2; ++k) dst[n][k] = *(const PG8_LAS bf16x8*)(lds + PG8_SB(b, h) + boff + n * 2048 + k * 1024); } while (0)
; #define PG8_MMA(ai, bj, At, Bt) do { __builtin_amdgcn_s_setprio(1); _Pragma("unroll") for (int m = 0; m < 4; ++m) _Pragma("unroll") for (int n = 0; n < 2; ++n) _Pragma("unroll") for (int k = 0; k < 2; ++k) \
;         acc[ai][bj][m][n] = __builtin_amdgcn_mfma_f32_16x16x32_bf16(Bt[n][k], At[m][k], acc[ai][bj][m][n], 0, 0, 0); __builtin_amdgcn_s_setprio(0); } while (0)
; #define PG8_WAIT_V(n) asm volatile("s_waitcnt vmcnt(" #n ")" ::: "memory")
; #define PG8_WAIT_L(n) asm volatile("s_waitcnt lgkmcnt(" #n ")" ::: "memory")
; #define PG8_BAR __builtin_amdgcn_s_barrier()
; #define PG8_SCHED __builtin_amdgcn_sched_barrier(0)
; template <class Epi, class Sched, bool ALIGN_EPI = false, bool SP2 = false>
; __device__ __forceinline__ void gemm_phase(PG8_LAS unsigned char* lds, const Gemm g, const Sched& S, const Epi& E) {
;     ...
;             PG8_WAIT_V(8); PG8_WAIT_L(0); PG8_BAR; PG8_MMA(1, 0, At, B0); PG8_MMA(1, 1, At, B1); PG8_BAR; PG8_SCHED;
;             PG8_LDB(B0, 1, 0); PG8_LDB(B1, 1, 1); PG8_SCHED; PG8_LDA(At, 1, 0); PG8_STAGE(PG8_SA(0, 1), a2 + hstep, voffA);
;             PG8_WAIT_V(8); PG8_WAIT_L(0); PG8_BAR; PG8_MMA(0, 0, At, B0); PG8_MMA(0, 1, At, B1); PG8_BAR; PG8_SCHED;
	s_setprio 1
	s_waitcnt lgkmcnt(0)
	v_mfma_f32_16x16x32_bf16 v[62:65], v[110:113], v[162:165], v[62:65]
	v_mfma_f32_16x16x32_bf16 v[62:65], v[118:121], v[166:169], v[62:65]
	v_mfma_f32_16x16x32_bf16 v[54:57], v[146:149], v[162:165], v[54:57]
	v_mfma_f32_16x16x32_bf16 v[54:57], v[150:153], v[166:169], v[54:57]
	v_mfma_f32_16x16x32_bf16 v[46:49], v[110:113], v[170:173], v[46:49]
	v_mfma_f32_16x16x32_bf16 v[46:49], v[118:121], v[174:177], v[46:49]
	v_mfma_f32_16x16x32_bf16 v[38:41], v[146:149], v[170:173], v[38:41]
	v_mfma_f32_16x16x32_bf16 v[38:41], v[150:153], v[174:177], v[38:41]
	v_mfma_f32_16x16x32_bf16 v[30:33], v[110:113], v[178:181], v[30:33]
	v_mfma_f32_16x16x32_bf16 v[30:33], v[118:121], v[182:185], v[30:33]
	v_mfma_f32_16x16x32_bf16 v[22:25], v[146:149], v[178:181], v[22:25]
	v_mfma_f32_16x16x32_bf16 v[22:25], v[150:153], v[182:185], v[22:25]
	v_mfma_f32_16x16x32_bf16 v[14:17], v[110:113], v[186:189], v[14:17]
	v_mfma_f32_16x16x32_bf16 v[14:17], v[118:121], v[190:193], v[14:17]
	v_mfma_f32_16x16x32_bf16 v[6:9], v[146:149], v[186:189], v[6:9]
	v_mfma_f32_16x16x32_bf16 v[6:9], v[150:153], v[190:193], v[6:9]
	v_mfma_f32_16x16x32_bf16 v[58:61], v[138:141], v[162:165], v[58:61]
	v_mfma_f32_16x16x32_bf16 v[58:61], v[142:145], v[166:169], v[58:61]
	v_mfma_f32_16x16x32_bf16 v[50:53], v[154:157], v[162:165], v[50:53]
	v_mfma_f32_16x16x32_bf16 v[50:53], v[158:161], v[166:169], v[50:53]
	v_mfma_f32_16x16x32_bf16 v[42:45], v[138:141], v[170:173], v[42:45]
	v_mfma_f32_16x16x32_bf16 v[42:45], v[142:145], v[174:177], v[42:45]
	v_mfma_f32_16x16x32_bf16 v[34:37], v[154:157], v[170:173], v[34:37]
	v_mfma_f32_16x16x32_bf16 v[34:37], v[158:161], v[174:177], v[34:37]
	v_mfma_f32_16x16x32_bf16 v[26:29], v[138:141], v[178:181], v[26:29]
	v_mfma_f32_16x16x32_bf16 v[26:29], v[142:145], v[182:185], v[26:29]
	v_mfma_f32_16x16x32_bf16 v[18:21], v[154:157], v[178:181], v[18:21]
	v_mfma_f32_16x16x32_bf16 v[18:21], v[158:161], v[182:185], v[18:21]
	v_mfma_f32_16x16x32_bf16 v[10:13], v[138:141], v[186:189], v[10:13]
	v_mfma_f32_16x16x32_bf16 v[10:13], v[142:145], v[190:193], v[10:13]
	v_mfma_f32_16x16x32_bf16 v[2:5], v[154:157], v[186:189], v[2:5]
	v_mfma_f32_16x16x32_bf16 v[2:5], v[158:161], v[190:193], v[2:5]
	s_setprio 0
	s_barrier
	s_add_i32 s18, 0, 0x18000
	s_add_i32 vcc_hi, 0, 0x1c000
	v_add_u32_e32 v142, s18, v245
	v_add_u32_e32 v158, vcc_hi, v245
	ds_read_b128 v[110:113], v142
	ds_read_b128 v[118:121], v142 offset:1024
	ds_read_b128 v[138:141], v142 offset:2048
	ds_read_b128 v[142:145], v142 offset:3072
	ds_read_b128 v[146:149], v158
	ds_read_b128 v[150:153], v158 offset:1024
	ds_read_b128 v[154:157], v158 offset:2048
	ds_read_b128 v[158:161], v158 offset:3072
	s_add_u32 s38, s46, s58
	s_addc_u32 s39, s47, 0
	s_mov_b32 m0, s94
	v_lshl_add_u64 v[222:223], s[38:39], 0, v[194:195]
	ds_read_b128 v[162:165], v247 offset:32768
	ds_read_b128 v[166:169], v247 offset:33792
	ds_read_b128 v[170:173], v247 offset:34816
	ds_read_b128 v[174:177], v247 offset:35840
	ds_read_b128 v[178:181], v247 offset:36864
	ds_read_b128 v[182:185], v247 offset:37888
	ds_read_b128 v[186:189], v247 offset:38912
	ds_read_b128 v[190:193], v247 offset:39936
	global_load_lds_dwordx4 v[222:223], off
	v_lshl_add_u64 v[222:223], s[38:39], 0, v[202:203]
	s_mov_b32 m0, s95
	s_nop 0
	global_load_lds_dwordx4 v[222:223], off
	s_waitcnt vmcnt(8)
	s_waitcnt lgkmcnt(0)
	s_barrier
	s_setprio 1
	s_waitcnt lgkmcnt(0)
	v_mfma_f32_16x16x32_bf16 v[130:133], v[110:113], v[162:165], v[130:133]
	v_mfma_f32_16x16x32_bf16 v[130:133], v[118:121], v[166:169], v[130:133]
	v_mfma_f32_16x16x32_bf16 v[126:129], v[146:149], v[162:165], v[126:129]
	v_mfma_f32_16x16x32_bf16 v[126:129], v[150:153], v[166:169], v[126:129]
	v_mfma_f32_16x16x32_bf16 v[114:117], v[110:113], v[170:173], v[114:117]
	v_mfma_f32_16x16x32_bf16 v[114:117], v[118:121], v[174:177], v[114:117]
	v_mfma_f32_16x16x32_bf16 v[102:105], v[146:149], v[170:173], v[102:105]
	v_mfma_f32_16x16x32_bf16 v[102:105], v[150:153], v[174:177], v[102:105]
	v_mfma_f32_16x16x32_bf16 v[94:97], v[110:113], v[178:181], v[94:97]
	v_mfma_f32_16x16x32_bf16 v[94:97], v[118:121], v[182:185], v[94:97]
	v_mfma_f32_16x16x32_bf16 v[86:89], v[146:149], v[178:181], v[86:89]
	v_mfma_f32_16x16x32_bf16 v[86:89], v[150:153], v[182:185], v[86:89]
	v_mfma_f32_16x16x32_bf16 v[78:81], v[110:113], v[186:189], v[78:81]
	v_mfma_f32_16x16x32_bf16 v[78:81], v[118:121], v[190:193], v[78:81]
	v_mfma_f32_16x16x32_bf16 v[70:73], v[146:149], v[186:189], v[70:73]
	v_mfma_f32_16x16x32_bf16 v[70:73], v[150:153], v[190:193], v[70:73]
	v_mfma_f32_16x16x32_bf16 v[134:137], v[138:141], v[162:165], v[134:137]
	v_mfma_f32_16x16x32_bf16 v[134:137], v[142:145], v[166:169], v[134:137]
	v_mfma_f32_16x16x32_bf16 v[122:125], v[154:157], v[162:165], v[122:125]
	v_mfma_f32_16x16x32_bf16 v[122:125], v[158:161], v[166:169], v[122:125]
	v_mfma_f32_16x16x32_bf16 v[106:109], v[138:141], v[170:173], v[106:109]
	v_mfma_f32_16x16x32_bf16 v[106:109], v[142:145], v[174:177], v[106:109]
	v_mfma_f32_16x16x32_bf16 v[98:101], v[154:157], v[170:173], v[98:101]
	v_mfma_f32_16x16x32_bf16 v[98:101], v[158:161], v[174:177], v[98:101]
	v_mfma_f32_16x16x32_bf16 v[90:93], v[138:141], v[178:181], v[90:93]
	v_mfma_f32_16x16x32_bf16 v[90:93], v[142:145], v[182:185], v[90:93]
	v_mfma_f32_16x16x32_bf16 v[82:85], v[154:157], v[178:181], v[82:85]
	v_mfma_f32_16x16x32_bf16 v[82:85], v[158:161], v[182:185], v[82:85]
	v_mfma_f32_16x16x32_bf16 v[74:77], v[138:141], v[186:189], v[74:77]
	v_mfma_f32_16x16x32_bf16 v[74:77], v[142:145], v[190:193], v[74:77]
	v_mfma_f32_16x16x32_bf16 v[66:69], v[154:157], v[186:189], v[66:69]
	v_mfma_f32_16x16x32_bf16 v[66:69], v[158:161], v[190:193], v[66:69]
	s_setprio 0
	s_barrier
; #define PG8_STAGE(bufoff, gbase, voff) do { _Pragma("unroll") for (int _i = 0; _i < 2; ++_i) \
;         __builtin_amdgcn_global_load_lds((const unsigned*)((const char*)(gbase) + (voff)[_i]), (PG8_LAS unsigned*)(lds + (bufoff) + ldsw + _i * 8192), 16, 0, 0); } while (0)
; #define PG8_LDA(dst, b, h) do { _Pragma("unroll") for (int m = 0; m < 4; ++m) _Pragma("unroll") for (int k = 0; k < 2; ++k) dst[m][k] = *(const PG8_LAS bf16x8*)(lds + PG8_SA(b, h) + aoff + m * 2048 + k * 1024); } while (0)
; #define PG8_MMA(ai, bj, At, Bt) do { __builtin_amdgcn_s_setprio(1); _Pragma("unroll") for (int m = 0; m < 4; ++m) _Pragma("unroll") for (int n = 0; n < 2; ++n) _Pragma("unroll") for (int k = 0; k < 2; ++k) \
;         acc[ai][bj][m][n] = __builtin_amdgcn_mfma_f32_16x16x32_bf16(Bt[n][k], At[m][k], acc[ai][bj][m][n], 0, 0, 0); __builtin_amdgcn_s_setprio(0); } while (0)
; #define PG8_WAIT_V(n) asm volatile("s_waitcnt vmcnt(" #n ")" ::: "memory")
; #define PG8_WAIT_L(n) asm volatile("s_waitcnt lgkmcnt(" #n ")" ::: "memory")
; #define PG8_BAR __builtin_amdgcn_s_barrier()
; #define PG8_SCHED __builtin_amdgcn_sched_barrier(0)
; template <class Epi, class Sched, bool ALIGN_EPI = false, bool SP2 = false>
; __device__ __forceinline__ void gemm_phase(PG8_LAS unsigned char* lds, const Gemm g, const Sched& S, const Epi& E) {
;     ...
;             PG8_LDA(At, 1, 1); PG8_STAGE(PG8_SB(1, 0), b3, voffB); PG8_STAGE(PG8_SB(1, 1), b3 + hstep, voffB); PG8_STAGE(PG8_SA(1, 0), a3, voffA);
;             PG8_WAIT_V(8); PG8_WAIT_L(0); PG8_BAR; PG8_MMA(1, 0, At, B0); PG8_MMA(1, 1, At, B1); PG8_BAR; PG8_SCHED;
	s_add_i32 s18, s18, s6
	v_lshl_add_u64 v[210:211], v[210:211], 0, s[30:31]
	s_mov_b32 m0, s18
	ds_read_b128 v[162:165], v247 offset:49152
	ds_read_b128 v[166:169], v247 offset:50176
	ds_read_b128 v[170:173], v247 offset:51200
	ds_read_b128 v[174:177], v247 offset:52224
	ds_read_b128 v[178:181], v247 offset:53248
	ds_read_b128 v[182:185], v247 offset:54272
	ds_read_b128 v[186:189], v247 offset:55296
	ds_read_b128 v[190:193], v247 offset:56320
	global_load_lds_dwordx4 v[210:211], off
	v_lshl_add_u64 v[210:211], v[212:213], 0, s[30:31]
	s_add_i32 m0, s18, 0x2000
	s_add_i32 s18, vcc_hi, s6
	global_load_lds_dwordx4 v[210:211], off
	v_lshl_add_u64 v[210:211], v[214:215], 0, s[30:31]
	s_mov_b32 m0, s18
	s_nop 0
	global_load_lds_dwordx4 v[210:211], off
	v_lshl_add_u64 v[210:211], v[216:217], 0, s[30:31]
	s_add_i32 m0, s18, 0x2000
	s_nop 0
	global_load_lds_dwordx4 v[210:211], off
	v_lshl_add_u64 v[210:211], v[218:219], 0, s[30:31]
	s_mov_b32 m0, s97
	s_nop 0
	global_load_lds_dwordx4 v[210:211], off
	v_lshl_add_u64 v[210:211], v[220:221], 0, s[30:31]
	s_mov_b32 m0, s98
	s_nop 0
	global_load_lds_dwordx4 v[210:211], off
	s_waitcnt vmcnt(8)
	s_waitcnt lgkmcnt(0)
	s_barrier
	s_setprio 1
	s_waitcnt lgkmcnt(0)
	v_mfma_f32_16x16x32_bf16 v[62:65], v[110:113], v[162:165], v[62:65]
	v_mfma_f32_16x16x32_bf16 v[62:65], v[118:121], v[166:169], v[62:65]
	v_mfma_f32_16x16x32_bf16 v[54:57], v[146:149], v[162:165], v[54:57]
	v_mfma_f32_16x16x32_bf16 v[54:57], v[150:153], v[166:169], v[54:57]
	v_mfma_f32_16x16x32_bf16 v[46:49], v[110:113], v[170:173], v[46:49]
	v_mfma_f32_16x16x32_bf16 v[46:49], v[118:121], v[174:177], v[46:49]
	v_mfma_f32_16x16x32_bf16 v[38:41], v[146:149], v[170:173], v[38:41]
	v_mfma_f32_16x16x32_bf16 v[38:41], v[150:153], v[174:177], v[38:41]
	v_mfma_f32_16x16x32_bf16 v[30:33], v[110:113], v[178:181], v[30:33]
	v_mfma_f32_16x16x32_bf16 v[30:33], v[118:121], v[182:185], v[30:33]
	v_mfma_f32_16x16x32_bf16 v[22:25], v[146:149], v[178:181], v[22:25]
	v_mfma_f32_16x16x32_bf16 v[22:25], v[150:153], v[182:185], v[22:25]
	v_mfma_f32_16x16x32_bf16 v[14:17], v[110:113], v[186:189], v[14:17]
	v_mfma_f32_16x16x32_bf16 v[14:17], v[118:121], v[190:193], v[14:17]
	v_mfma_f32_16x16x32_bf16 v[6:9], v[146:149], v[186:189], v[6:9]
	v_mfma_f32_16x16x32_bf16 v[6:9], v[150:153], v[190:193], v[6:9]
	v_mfma_f32_16x16x32_bf16 v[58:61], v[138:141], v[162:165], v[58:61]
	v_mfma_f32_16x16x32_bf16 v[58:61], v[142:145], v[166:169], v[58:61]
	v_mfma_f32_16x16x32_bf16 v[50:53], v[154:157], v[162:165], v[50:53]
	v_mfma_f32_16x16x32_bf16 v[50:53], v[158:161], v[166:169], v[50:53]
	v_mfma_f32_16x16x32_bf16 v[42:45], v[138:141], v[170:173], v[42:45]
	v_mfma_f32_16x16x32_bf16 v[42:45], v[142:145], v[174:177], v[42:45]
	v_mfma_f32_16x16x32_bf16 v[34:37], v[154:157], v[170:173], v[34:37]
	v_mfma_f32_16x16x32_bf16 v[34:37], v[158:161], v[174:177], v[34:37]
	v_mfma_f32_16x16x32_bf16 v[26:29], v[138:141], v[178:181], v[26:29]
	v_mfma_f32_16x16x32_bf16 v[26:29], v[142:145], v[182:185], v[26:29]
	v_mfma_f32_16x16x32_bf16 v[18:21], v[154:157], v[178:181], v[18:21]
	v_mfma_f32_16x16x32_bf16 v[18:21], v[158:161], v[182:185], v[18:21]
	v_mfma_f32_16x16x32_bf16 v[10:13], v[138:141], v[186:189], v[10:13]
	v_mfma_f32_16x16x32_bf16 v[10:13], v[142:145], v[190:193], v[10:13]
	v_mfma_f32_16x16x32_bf16 v[2:5], v[154:157], v[186:189], v[2:5]
	v_mfma_f32_16x16x32_bf16 v[2:5], v[158:161], v[190:193], v[2:5]
	s_setprio 0
	s_barrier
	s_add_u32 s48, s48, 0x100
	s_addc_u32 s49, s49, 0
	s_add_u32 s50, s50, 0x100
	s_addc_u32 s51, s51, 0
	s_cmp_ge_u32 vcc_lo, s96
	s_mov_b32 s46, vcc_lo
	s_cbranch_scc0 .LBB0_274
	s_and_b64 vcc, exec, s[72:73]
	s_cbranch_vccz .LBB0_277
	s_barrier

; #define PG8_STAGE(bufoff, gbase, voff) do { _Pragma("unroll") for (int _i = 0; _i < 2; ++_i) \
;         __builtin_amdgcn_global_load_lds((const unsigned*)((const char*)(gbase) + (voff)[_i]), (PG8_LAS unsigned*)(lds + (bufoff) + ldsw + _i * 8192), 16, 0, 0); } while (0)
; #define PG8_LDA(dst, b, h) do { _Pragma("unroll") for (int m = 0; m < 4; ++m) _Pragma("unroll") for (int k = 0; k < 2; ++k) dst[m][k] = *(const PG8_LAS bf16x8*)(lds + PG8_SA(b, h) + aoff + m * 2048 + k * 1024); } while (0)
; #define PG8_LDB(dst, b, h) do { _Pragma("unroll") for (int n = 0; n < 2; ++n) _Pragma("unroll") for (int k = 0; k < 2; ++k) dst[n][k] = *(const PG8_LAS bf16x8*)(lds + PG8_SB(b, h) + boff + n * 2048 + k * 1024); } while (0)
; #define PG8_MMA(ai, bj, At, Bt) do { __builtin_amdgcn_s_setprio(1); _Pragma("unroll") for (int m = 0; m < 4; ++m) _Pragma("unroll") for (int n = 0; n < 2; ++n) _Pragma("unroll") for (int k = 0; k < 2; ++k) \
;         acc[ai][bj][m][n] = __builtin_amdgcn_mfma_f32_16x16x32_bf16(Bt[n][k], At[m][k], acc[ai][bj][m][n], 0, 0, 0); __builtin_amdgcn_s_setprio(0); } while (0)
; #define PG8_WAIT_V(n) asm volatile("s_waitcnt vmcnt(" #n ")" ::: "memory")
; #define PG8_WAIT_L(n) asm volatile("s_waitcnt lgkmcnt(" #n ")" ::: "memory")
; template <class Epi, class Sched, bool ALIGN_EPI = false, bool SP2 = false>
; __device__ __forceinline__ void gemm_phase(PG8_LAS unsigned char* lds, const Gemm g, const Sched& S, const Epi& E) {
;     ...
;             const bool last = (t == nt - 2);
;             const char* a1 = cA + (size_t)(t + 1) * kstep;
;             const char* a2 = last ? nA : cA + (size_t)(t + 2) * kstep; const char* b2 = last ? nB : cB + (size_t)(t + 2) * kstep;
;             const char* a3 = a2 + kstep; const char* b3 = b2 + kstep;
;             if (last && has_next) S.a_ready(nxt);
;             if constexpr (SP2) {
;             PG8_LDB(B0, 0, 0); PG8_LDB(B1, 0, 1); PG8_SCHED; PG8_LDA(At, 0, 0); PG8_STAGE(PG8_SA(1, 1), a1 + hstep, voffA);
;             PG8_WAIT_V(8); PG8_WAIT_L(0); PG8_BAR; PG8_MMA(0, 0, At, B0); PG8_MMA(0, 1, At, B1); PG8_BAR; PG8_SCHED;
;             PG8_LDA(At, 0, 1); PG8_STAGE(PG8_SB(0, 0), b2, voffB); PG8_STAGE(PG8_SB(0, 1), b2 + hstep, voffB); PG8_STAGE(PG8_SA(0, 0), a2, voffA);
;             PG8_WAIT_V(8); PG8_WAIT_L(0); PG8_BAR; PG8_MMA(1, 0, At, B0); PG8_MMA(1, 1, At, B1); PG8_BAR; PG8_SCHED;
.LBB0_408:
	s_add_u32 s38, s48, 0xfffc0080
	s_addc_u32 s39, s49, -1
	s_add_i32 s85, 0, 0x10000
	s_cmp_eq_u32 s84, 12
	s_cselect_b32 s73, s21, s39
	s_cselect_b32 s72, s27, s38
	v_add_u32_e32 v0, s85, v167
	s_cselect_b32 s47, s29, s69
	s_cselect_b32 s46, s33, s53
	s_add_i32 s38, 0, 0x14000
	ds_read_b128 v[142:145], v0
	ds_read_b128 v[146:149], v0 offset:1024
	ds_read_b128 v[150:153], v0 offset:2048
	ds_read_b128 v[154:157], v0 offset:3072
	v_add_u32_e32 v0, s38, v167
	ds_read_b128 v[158:161], v0
	ds_read_b128 v[162:165], v0 offset:1024
	ds_read_b128 v[172:175], v0 offset:2048
	ds_read_b128 v[176:179], v0 offset:3072
	v_lshl_add_u64 v[218:219], s[48:49], 0, v[138:139]
	s_add_i32 m0, s76, 0xc000
	ds_read_b128 v[180:183], v170
	ds_read_b128 v[184:187], v170 offset:1024
	ds_read_b128 v[188:191], v170 offset:2048
	ds_read_b128 v[192:195], v170 offset:3072
	ds_read_b128 v[202:205], v170 offset:4096
	ds_read_b128 v[206:209], v170 offset:5120
	ds_read_b128 v[210:213], v170 offset:6144
	ds_read_b128 v[214:217], v170 offset:7168
	global_load_lds_dwordx4 v[218:219], off
	v_lshl_add_u64 v[218:219], s[48:49], 0, v[140:141]
	s_add_i32 m0, s76, 0xe000
	s_nop 0
	global_load_lds_dwordx4 v[218:219], off
	s_waitcnt vmcnt(8)
	s_waitcnt lgkmcnt(0)
	s_barrier
	s_setprio 1
	s_waitcnt lgkmcnt(0)
	v_mfma_f32_16x16x32_bf16 v[122:125], v[142:145], v[180:183], v[122:125]
	v_mfma_f32_16x16x32_bf16 v[122:125], v[146:149], v[184:187], v[122:125]
	v_mfma_f32_16x16x32_bf16 v[114:117], v[158:161], v[180:183], v[114:117]
	v_mfma_f32_16x16x32_bf16 v[114:117], v[162:165], v[184:187], v[114:117]
	v_mfma_f32_16x16x32_bf16 v[106:109], v[142:145], v[188:191], v[106:109]
	v_mfma_f32_16x16x32_bf16 v[106:109], v[146:149], v[192:195], v[106:109]
	v_mfma_f32_16x16x32_bf16 v[98:101], v[158:161], v[188:191], v[98:101]
	v_mfma_f32_16x16x32_bf16 v[98:101], v[162:165], v[192:195], v[98:101]
	v_mfma_f32_16x16x32_bf16 v[90:93], v[142:145], v[202:205], v[90:93]
	v_mfma_f32_16x16x32_bf16 v[90:93], v[146:149], v[206:209], v[90:93]
	v_mfma_f32_16x16x32_bf16 v[82:85], v[158:161], v[202:205], v[82:85]
	v_mfma_f32_16x16x32_bf16 v[82:85], v[162:165], v[206:209], v[82:85]
	v_mfma_f32_16x16x32_bf16 v[74:77], v[142:145], v[210:213], v[74:77]
	v_mfma_f32_16x16x32_bf16 v[74:77], v[146:149], v[214:217], v[74:77]
	v_mfma_f32_16x16x32_bf16 v[66:69], v[158:161], v[210:213], v[66:69]
	v_mfma_f32_16x16x32_bf16 v[66:69], v[162:165], v[214:217], v[66:69]
	v_mfma_f32_16x16x32_bf16 v[126:129], v[150:153], v[180:183], v[126:129]
	v_mfma_f32_16x16x32_bf16 v[126:129], v[154:157], v[184:187], v[126:129]
	v_mfma_f32_16x16x32_bf16 v[118:121], v[172:175], v[180:183], v[118:121]
	v_mfma_f32_16x16x32_bf16 v[118:121], v[176:179], v[184:187], v[118:121]
	v_mfma_f32_16x16x32_bf16 v[110:113], v[150:153], v[188:191], v[110:113]
	v_mfma_f32_16x16x32_bf16 v[110:113], v[154:157], v[192:195], v[110:113]
	v_mfma_f32_16x16x32_bf16 v[102:105], v[172:175], v[188:191], v[102:105]
	v_mfma_f32_16x16x32_bf16 v[102:105], v[176:179], v[192:195], v[102:105]
	v_mfma_f32_16x16x32_bf16 v[94:97], v[150:153], v[202:205], v[94:97]
	v_mfma_f32_16x16x32_bf16 v[94:97], v[154:157], v[206:209], v[94:97]
	v_mfma_f32_16x16x32_bf16 v[86:89], v[172:175], v[202:205], v[86:89]
	v_mfma_f32_16x16x32_bf16 v[86:89], v[176:179], v[206:209], v[86:89]
	v_mfma_f32_16x16x32_bf16 v[78:81], v[150:153], v[210:213], v[78:81]
	v_mfma_f32_16x16x32_bf16 v[78:81], v[154:157], v[214:217], v[78:81]
	v_mfma_f32_16x16x32_bf16 v[70:73], v[172:175], v[210:213], v[70:73]
	v_mfma_f32_16x16x32_bf16 v[70:73], v[176:179], v[214:217], v[70:73]
	s_setprio 0
	s_barrier
	s_add_i32 s39, s85, s75
	v_lshl_add_u64 v[218:219], s[46:47], 0, v[134:135]
	s_mov_b32 m0, s39
	ds_read_b128 v[180:183], v170 offset:16384
	ds_read_b128 v[184:187], v170 offset:17408
	ds_read_b128 v[188:191], v170 offset:18432
	ds_read_b128 v[192:195], v170 offset:19456
	ds_read_b128 v[202:205], v170 offset:20480
	ds_read_b128 v[206:209], v170 offset:21504
	ds_read_b128 v[210:213], v170 offset:22528
	ds_read_b128 v[214:217], v170 offset:23552
	global_load_lds_dwordx4 v[218:219], off
	s_add_i32 m0, s39, 0x2000
	s_add_u32 s92, s46, 0x40000
	v_lshl_add_u64 v[220:221], s[46:47], 0, v[130:131]
	s_addc_u32 s93, s47, 0
	s_add_i32 s38, s38, s75
	global_load_lds_dwordx4 v[220:221], off
	v_lshl_add_u64 v[222:223], s[92:93], 0, v[134:135]
	s_mov_b32 m0, s38
	v_lshl_add_u64 v[224:225], s[72:73], 0, v[132:133]
	global_load_lds_dwordx4 v[222:223], off
	v_lshl_add_u64 v[222:223], s[92:93], 0, v[130:131]
	s_add_i32 m0, s38, 0x2000
	s_nop 0
	global_load_lds_dwordx4 v[222:223], off
	v_lshl_add_u64 v[222:223], s[72:73], 0, v[136:137]
	s_mov_b32 m0, s76
	s_nop 0
	global_load_lds_dwordx4 v[222:223], off
	s_mov_b32 m0, s77
	s_nop 0
	global_load_lds_dwordx4 v[224:225], off
	s_waitcnt vmcnt(8)
	s_waitcnt lgkmcnt(0)
	s_barrier
; #define PG8_STAGE(bufoff, gbase, voff) do { _Pragma("unroll") for (int _i = 0; _i < 2; ++_i) \
;         __builtin_amdgcn_global_load_lds((const unsigned*)((const char*)(gbase) + (voff)[_i]), (PG8_LAS unsigned*)(lds + (bufoff) + ldsw + _i * 8192), 16, 0, 0); } while (0)
; #define PG8_LDA(dst, b, h) do { _Pragma("unroll") for (int m = 0; m < 4; ++m) _Pragma("unroll") for (int k = 0; k < 2; ++k) dst[m][k] = *(const PG8_LAS bf16x8*)(lds + PG8_SA(b, h) + aoff + m * 2048 + k * 1024); } while (0)
; #define PG8_LDB(dst, b, h) do { _Pragma("unroll") for (int n = 0; n < 2; ++n) _Pragma("unroll") for (int k = 0; k < 2; ++k) dst[n][k] = *(const PG8_LAS bf16x8*)(lds + PG8_SB(b, h) + boff + n * 2048 + k * 1024); } while (0)
; #define PG8_MMA(ai, bj, At, Bt) do { __builtin_amdgcn_s_setprio(1); _Pragma("unroll") for (int m = 0; m < 4; ++m) _Pragma("unroll") for (int n = 0; n < 2; ++n) _Pragma("unroll") for (int k = 0; k < 2; ++k) \
;         acc[ai][bj][m][n] = __builtin_amdgcn_mfma_f32_16x16x32_bf16(Bt[n][k], At[m][k], acc[ai][bj][m][n], 0, 0, 0); __builtin_amdgcn_s_setprio(0); } while (0)
; #define PG8_WAIT_V(n) asm volatile("s_waitcnt vmcnt(" #n ")" ::: "memory")
; #define PG8_WAIT_L(n) asm volatile("s_waitcnt lgkmcnt(" #n ")" ::: "memory")
; #define PG8_BAR __builtin_amdgcn_s_barrier()
; #define PG8_SCHED __builtin_amdgcn_sched_barrier(0)
; template <class Epi, class Sched, bool ALIGN_EPI = false, bool SP2 = false>
; __device__ __forceinline__ void gemm_phase(PG8_LAS unsigned char* lds, const Gemm g, const Sched& S, const Epi& E) {
;     ...
;             PG8_WAIT_V(8); PG8_WAIT_L(0); PG8_BAR; PG8_MMA(1, 0, At, B0); PG8_MMA(1, 1, At, B1); PG8_BAR; PG8_SCHED;
;             PG8_LDB(B0, 1, 0); PG8_LDB(B1, 1, 1); PG8_SCHED; PG8_LDA(At, 1, 0); PG8_STAGE(PG8_SA(0, 1), a2 + hstep, voffA);
;             PG8_WAIT_V(8); PG8_WAIT_L(0); PG8_BAR; PG8_MMA(0, 0, At, B0); PG8_MMA(0, 1, At, B1); PG8_BAR; PG8_SCHED;
	s_setprio 1
	s_waitcnt lgkmcnt(0)
	v_mfma_f32_16x16x32_bf16 v[58:61], v[142:145], v[180:183], v[58:61]
	v_mfma_f32_16x16x32_bf16 v[58:61], v[146:149], v[184:187], v[58:61]
	v_mfma_f32_16x16x32_bf16 v[50:53], v[158:161], v[180:183], v[50:53]
	v_mfma_f32_16x16x32_bf16 v[50:53], v[162:165], v[184:187], v[50:53]
	v_mfma_f32_16x16x32_bf16 v[42:45], v[142:145], v[188:191], v[42:45]
	v_mfma_f32_16x16x32_bf16 v[42:45], v[146:149], v[192:195], v[42:45]
	v_mfma_f32_16x16x32_bf16 v[34:37], v[158:161], v[188:191], v[34:37]
	v_mfma_f32_16x16x32_bf16 v[34:37], v[162:165], v[192:195], v[34:37]
	v_mfma_f32_16x16x32_bf16 v[26:29], v[142:145], v[202:205], v[26:29]
	v_mfma_f32_16x16x32_bf16 v[26:29], v[146:149], v[206:209], v[26:29]
	v_mfma_f32_16x16x32_bf16 v[18:21], v[158:161], v[202:205], v[18:21]
	v_mfma_f32_16x16x32_bf16 v[18:21], v[162:165], v[206:209], v[18:21]
	v_mfma_f32_16x16x32_bf16 v[10:13], v[142:145], v[210:213], v[10:13]
	v_mfma_f32_16x16x32_bf16 v[10:13], v[146:149], v[214:217], v[10:13]
	v_mfma_f32_16x16x32_bf16 v[2:5], v[158:161], v[210:213], v[2:5]
	v_mfma_f32_16x16x32_bf16 v[2:5], v[162:165], v[214:217], v[2:5]
	v_mfma_f32_16x16x32_bf16 v[62:65], v[150:153], v[180:183], v[62:65]
	v_mfma_f32_16x16x32_bf16 v[62:65], v[154:157], v[184:187], v[62:65]
	v_mfma_f32_16x16x32_bf16 v[54:57], v[172:175], v[180:183], v[54:57]
	v_mfma_f32_16x16x32_bf16 v[54:57], v[176:179], v[184:187], v[54:57]
	v_mfma_f32_16x16x32_bf16 v[46:49], v[150:153], v[188:191], v[46:49]
	v_mfma_f32_16x16x32_bf16 v[46:49], v[154:157], v[192:195], v[46:49]
	v_mfma_f32_16x16x32_bf16 v[38:41], v[172:175], v[188:191], v[38:41]
	v_mfma_f32_16x16x32_bf16 v[38:41], v[176:179], v[192:195], v[38:41]
	v_mfma_f32_16x16x32_bf16 v[30:33], v[150:153], v[202:205], v[30:33]
	v_mfma_f32_16x16x32_bf16 v[30:33], v[154:157], v[206:209], v[30:33]
	v_mfma_f32_16x16x32_bf16 v[22:25], v[172:175], v[202:205], v[22:25]
	v_mfma_f32_16x16x32_bf16 v[22:25], v[176:179], v[206:209], v[22:25]
	v_mfma_f32_16x16x32_bf16 v[14:17], v[150:153], v[210:213], v[14:17]
	v_mfma_f32_16x16x32_bf16 v[14:17], v[154:157], v[214:217], v[14:17]
	v_mfma_f32_16x16x32_bf16 v[6:9], v[172:175], v[210:213], v[6:9]
	v_mfma_f32_16x16x32_bf16 v[6:9], v[176:179], v[214:217], v[6:9]
	s_setprio 0
	s_barrier
	s_add_i32 s38, 0, 0x18000
	v_add_u32_e32 v0, s38, v167
	s_add_i32 s39, 0, 0x1c000
	ds_read_b128 v[142:145], v0
	ds_read_b128 v[146:149], v0 offset:1024
	ds_read_b128 v[150:153], v0 offset:2048
	ds_read_b128 v[154:157], v0 offset:3072
	v_add_u32_e32 v0, s39, v167
	ds_read_b128 v[158:161], v0
	ds_read_b128 v[162:165], v0 offset:1024
	ds_read_b128 v[172:175], v0 offset:2048
	ds_read_b128 v[176:179], v0 offset:3072
	s_add_u32 s72, s72, 0x40000
	s_addc_u32 s73, s73, 0
	s_mov_b32 m0, s78
	v_lshl_add_u64 v[226:227], s[72:73], 0, v[136:137]
	ds_read_b128 v[180:183], v170 offset:32768
	ds_read_b128 v[184:187], v170 offset:33792
	ds_read_b128 v[188:191], v170 offset:34816
	ds_read_b128 v[192:195], v170 offset:35840
	ds_read_b128 v[202:205], v170 offset:36864
	ds_read_b128 v[206:209], v170 offset:37888
	ds_read_b128 v[210:213], v170 offset:38912
	ds_read_b128 v[214:217], v170 offset:39936
	global_load_lds_dwordx4 v[226:227], off
	v_lshl_add_u64 v[226:227], s[72:73], 0, v[132:133]
	s_mov_b32 m0, s79
	s_nop 0
	global_load_lds_dwordx4 v[226:227], off
	s_waitcnt vmcnt(8)
	s_waitcnt lgkmcnt(0)
	s_barrier
	s_setprio 1
	s_waitcnt lgkmcnt(0)
	v_mfma_f32_16x16x32_bf16 v[122:125], v[142:145], v[180:183], v[122:125]
	v_mfma_f32_16x16x32_bf16 v[122:125], v[146:149], v[184:187], v[122:125]
	v_mfma_f32_16x16x32_bf16 v[114:117], v[158:161], v[180:183], v[114:117]
	v_mfma_f32_16x16x32_bf16 v[114:117], v[162:165], v[184:187], v[114:117]
	v_mfma_f32_16x16x32_bf16 v[106:109], v[142:145], v[188:191], v[106:109]
	v_mfma_f32_16x16x32_bf16 v[106:109], v[146:149], v[192:195], v[106:109]
	v_mfma_f32_16x16x32_bf16 v[98:101], v[158:161], v[188:191], v[98:101]
	v_mfma_f32_16x16x32_bf16 v[98:101], v[162:165], v[192:195], v[98:101]
	v_mfma_f32_16x16x32_bf16 v[90:93], v[142:145], v[202:205], v[90:93]
	v_mfma_f32_16x16x32_bf16 v[90:93], v[146:149], v[206:209], v[90:93]
	v_mfma_f32_16x16x32_bf16 v[82:85], v[158:161], v[202:205], v[82:85]
	v_mfma_f32_16x16x32_bf16 v[82:85], v[162:165], v[206:209], v[82:85]
	v_mfma_f32_16x16x32_bf16 v[74:77], v[142:145], v[210:213], v[74:77]
	v_mfma_f32_16x16x32_bf16 v[74:77], v[146:149], v[214:217], v[74:77]
	v_mfma_f32_16x16x32_bf16 v[66:69], v[158:161], v[210:213], v[66:69]
	v_mfma_f32_16x16x32_bf16 v[66:69], v[162:165], v[214:217], v[66:69]
	v_mfma_f32_16x16x32_bf16 v[126:129], v[150:153], v[180:183], v[126:129]
	v_mfma_f32_16x16x32_bf16 v[126:129], v[154:157], v[184:187], v[126:129]
	v_mfma_f32_16x16x32_bf16 v[118:121], v[172:175], v[180:183], v[118:121]
	v_mfma_f32_16x16x32_bf16 v[118:121], v[176:179], v[184:187], v[118:121]
	v_mfma_f32_16x16x32_bf16 v[110:113], v[150:153], v[188:191], v[110:113]
	v_mfma_f32_16x16x32_bf16 v[110:113], v[154:157], v[192:195], v[110:113]
	v_mfma_f32_16x16x32_bf16 v[102:105], v[172:175], v[188:191], v[102:105]
	v_mfma_f32_16x16x32_bf16 v[102:105], v[176:179], v[192:195], v[102:105]
	v_mfma_f32_16x16x32_bf16 v[94:97], v[150:153], v[202:205], v[94:97]
	v_mfma_f32_16x16x32_bf16 v[94:97], v[154:157], v[206:209], v[94:97]
	v_mfma_f32_16x16x32_bf16 v[86:89], v[172:175], v[202:205], v[86:89]
	v_mfma_f32_16x16x32_bf16 v[86:89], v[176:179], v[206:209], v[86:89]
	v_mfma_f32_16x16x32_bf16 v[78:81], v[150:153], v[210:213], v[78:81]
	v_mfma_f32_16x16x32_bf16 v[78:81], v[154:157], v[214:217], v[78:81]
	v_mfma_f32_16x16x32_bf16 v[70:73], v[172:175], v[210:213], v[70:73]
	v_mfma_f32_16x16x32_bf16 v[70:73], v[176:179], v[214:217], v[70:73]
	s_setprio 0
	s_barrier
; #define PG8_STAGE(bufoff, gbase, voff) do { _Pragma("unroll") for (int _i = 0; _i < 2; ++_i) \
;         __builtin_amdgcn_global_load_lds((const unsigned*)((const char*)(gbase) + (voff)[_i]), (PG8_LAS unsigned*)(lds + (bufoff) + ldsw + _i * 8192), 16, 0, 0); } while (0)
; #define PG8_LDA(dst, b, h) do { _Pragma("unroll") for (int m = 0; m < 4; ++m) _Pragma("unroll") for (int k = 0; k < 2; ++k) dst[m][k] = *(const PG8_LAS bf16x8*)(lds + PG8_SA(b, h) + aoff + m * 2048 + k * 1024); } while (0)
; #define PG8_MMA(ai, bj, At, Bt) do { __builtin_amdgcn_s_setprio(1); _Pragma("unroll") for (int m = 0; m < 4; ++m) _Pragma("unroll") for (int n = 0; n < 2; ++n) _Pragma("unroll") for (int k = 0; k < 2; ++k) \
;         acc[ai][bj][m][n] = __builtin_amdgcn_mfma_f32_16x16x32_bf16(Bt[n][k], At[m][k], acc[ai][bj][m][n], 0, 0, 0); __builtin_amdgcn_s_setprio(0); } while (0)
; #define PG8_WAIT_V(n) asm volatile("s_waitcnt vmcnt(" #n ")" ::: "memory")
; #define PG8_WAIT_L(n) asm volatile("s_waitcnt lgkmcnt(" #n ")" ::: "memory")
; #define PG8_BAR __builtin_amdgcn_s_barrier()
; #define PG8_SCHED __builtin_amdgcn_sched_barrier(0)
; template <class Epi, class Sched, bool ALIGN_EPI = false, bool SP2 = false>
; __device__ __forceinline__ void gemm_phase(PG8_LAS unsigned char* lds, const Gemm g, const Sched& S, const Epi& E) {
;     ...
;             PG8_LDA(At, 1, 1); PG8_STAGE(PG8_SB(1, 0), b3, voffB); PG8_STAGE(PG8_SB(1, 1), b3 + hstep, voffB); PG8_STAGE(PG8_SA(1, 0), a3, voffA);
;             PG8_WAIT_V(8); PG8_WAIT_L(0); PG8_BAR; PG8_MMA(1, 0, At, B0); PG8_MMA(1, 1, At, B1); PG8_BAR; PG8_SCHED;
	s_add_i32 s38, s38, s75
	v_lshl_add_u64 v[218:219], v[218:219], 0, s[30:31]
	s_mov_b32 m0, s38
	ds_read_b128 v[180:183], v170 offset:49152
	ds_read_b128 v[184:187], v170 offset:50176
	ds_read_b128 v[188:191], v170 offset:51200
	ds_read_b128 v[192:195], v170 offset:52224
	ds_read_b128 v[202:205], v170 offset:53248
	ds_read_b128 v[206:209], v170 offset:54272
	ds_read_b128 v[210:213], v170 offset:55296
	ds_read_b128 v[214:217], v170 offset:56320
	global_load_lds_dwordx4 v[218:219], off
	s_add_i32 m0, s38, 0x2000
	s_add_u32 s46, s46, 0x40080
	v_lshl_add_u64 v[218:219], v[220:221], 0, s[30:31]
	s_addc_u32 s47, s47, 0
	s_add_i32 s38, s39, s75
	global_load_lds_dwordx4 v[218:219], off
	v_lshl_add_u64 v[218:219], s[46:47], 0, v[134:135]
	s_mov_b32 m0, s38
	s_nop 0
	global_load_lds_dwordx4 v[218:219], off
	v_lshl_add_u64 v[218:219], s[46:47], 0, v[130:131]
	s_add_i32 m0, s38, 0x2000
	s_nop 0
	global_load_lds_dwordx4 v[218:219], off
	v_lshl_add_u64 v[218:219], v[222:223], 0, s[30:31]
	s_mov_b32 m0, s80
	s_nop 0
	global_load_lds_dwordx4 v[218:219], off
	v_lshl_add_u64 v[218:219], v[224:225], 0, s[30:31]
	s_mov_b32 m0, s81
	s_nop 0
	global_load_lds_dwordx4 v[218:219], off
	s_waitcnt vmcnt(8)
	s_waitcnt lgkmcnt(0)
	s_barrier
	s_setprio 1
	s_waitcnt lgkmcnt(0)
	v_mfma_f32_16x16x32_bf16 v[58:61], v[142:145], v[180:183], v[58:61]
	v_mfma_f32_16x16x32_bf16 v[58:61], v[146:149], v[184:187], v[58:61]
	v_mfma_f32_16x16x32_bf16 v[50:53], v[158:161], v[180:183], v[50:53]
	v_mfma_f32_16x16x32_bf16 v[50:53], v[162:165], v[184:187], v[50:53]
	v_mfma_f32_16x16x32_bf16 v[42:45], v[142:145], v[188:191], v[42:45]
	v_mfma_f32_16x16x32_bf16 v[42:45], v[146:149], v[192:195], v[42:45]
	v_mfma_f32_16x16x32_bf16 v[34:37], v[158:161], v[188:191], v[34:37]
	v_mfma_f32_16x16x32_bf16 v[34:37], v[162:165], v[192:195], v[34:37]
	v_mfma_f32_16x16x32_bf16 v[26:29], v[142:145], v[202:205], v[26:29]
	v_mfma_f32_16x16x32_bf16 v[26:29], v[146:149], v[206:209], v[26:29]
	v_mfma_f32_16x16x32_bf16 v[18:21], v[158:161], v[202:205], v[18:21]
	v_mfma_f32_16x16x32_bf16 v[18:21], v[162:165], v[206:209], v[18:21]
	v_mfma_f32_16x16x32_bf16 v[10:13], v[142:145], v[210:213], v[10:13]
	v_mfma_f32_16x16x32_bf16 v[10:13], v[146:149], v[214:217], v[10:13]
	v_mfma_f32_16x16x32_bf16 v[2:5], v[158:161], v[210:213], v[2:5]
	v_mfma_f32_16x16x32_bf16 v[2:5], v[162:165], v[214:217], v[2:5]
	v_mfma_f32_16x16x32_bf16 v[62:65], v[150:153], v[180:183], v[62:65]
	v_mfma_f32_16x16x32_bf16 v[62:65], v[154:157], v[184:187], v[62:65]
	v_mfma_f32_16x16x32_bf16 v[54:57], v[172:175], v[180:183], v[54:57]
	v_mfma_f32_16x16x32_bf16 v[54:57], v[176:179], v[184:187], v[54:57]
	v_mfma_f32_16x16x32_bf16 v[46:49], v[150:153], v[188:191], v[46:49]
	v_mfma_f32_16x16x32_bf16 v[46:49], v[154:157], v[192:195], v[46:49]
	v_mfma_f32_16x16x32_bf16 v[38:41], v[172:175], v[188:191], v[38:41]
	v_mfma_f32_16x16x32_bf16 v[38:41], v[176:179], v[192:195], v[38:41]
	v_mfma_f32_16x16x32_bf16 v[30:33], v[150:153], v[202:205], v[30:33]
	v_mfma_f32_16x16x32_bf16 v[30:33], v[154:157], v[206:209], v[30:33]
	v_mfma_f32_16x16x32_bf16 v[22:25], v[172:175], v[202:205], v[22:25]
	v_mfma_f32_16x16x32_bf16 v[22:25], v[176:179], v[206:209], v[22:25]
	v_mfma_f32_16x16x32_bf16 v[14:17], v[150:153], v[210:213], v[14:17]
	v_mfma_f32_16x16x32_bf16 v[14:17], v[154:157], v[214:217], v[14:17]
	v_mfma_f32_16x16x32_bf16 v[6:9], v[172:175], v[210:213], v[6:9]
	v_mfma_f32_16x16x32_bf16 v[6:9], v[176:179], v[214:217], v[6:9]
	s_setprio 0
	s_barrier
	s_add_i32 s84, s84, 2
	s_add_u32 s48, s48, 0x100
	s_addc_u32 s49, s49, 0
	s_add_u32 s53, s53, 0x100
	s_addc_u32 s69, s69, 0
	s_cmp_gt_u32 s84, 13
	s_cbranch_scc0 .LBB0_408
	s_and_b64 vcc, exec, s[64:65]
	s_cbranch_vccz .LBB0_411
	s_barrier
